# attention loop shifted by one s_nop so the loop head sits on an 8-byte boundary (code placement)
# speedup vs baseline: 1.0048x; 1.0048x over previous
; #define SBAR() __builtin_amdgcn_sched_barrier(0)
; #define SLOAD(i, k0) do { sr_[i].vs0 = St::ld8(&Vh[(long)((k0) + sr) * LDK + sc]); sr_[i].vs1 = St::ld8(&Vh[(long)((k0) + 32 + sr) * LDK + sc]); \
;     sr_[i].ks0 = St::ld8(&Kh[(long)((k0) + sr) * LDK + sc]); sr_[i].ks1 = St::ld8(&Kh[(long)((k0) + 32 + sr) * LDK + sc]); } while (0)
; #define SWAIT() do { if constexpr (SDEPTH == 2) asm volatile("s_waitcnt vmcnt(4)" ::: "memory"); else asm volatile("s_waitcnt vmcnt(0)" ::: "memory"); } while (0)
; template <typename TQ> ...
;     ...
;   for (int j = 1; j + 1 < NT; j += 2) {
;     SBAR(); SLOAD(SO, (j + SDEPTH) * KVBLK); SBAR();
;     qkt(pB0, pB1, (bf16*)((char*)K_lds + SHM_K), qr, r32, hi, negm);
;     finishSM(pA0, pA1, l_reg, pa0, pa1, pa2, pa3); SBAR();
;     pv_d0(o, vb0, pa0, pa1, pa2, pa3); partialSM(pB0, pB1, mC);
;     __syncthreads(); SWAIT(); SWRITE(0, SE);
;     __syncthreads();
;     SBAR(); if (SDEPTH == 1 || j + 3 < NT) SLOAD(SE, (j + 1 + SDEPTH) * KVBLK); SBAR();
;     qkt(pA0, pA1, K_lds, qr, r32, hi, negm);
;     finishSM(pB0, pB1, l_reg, pa0, pa1, pa2, pa3); SBAR();
;     pv_d0(o, vb0 + (int)SHM_V, pa0, pa1, pa2, pa3); partialSM(pA0, pA1, mC);
;     __syncthreads(); SWAIT(); SWRITE(1, SO);
;     __syncthreads();
;   }
.Lattn_noprio:
	s_mov_b32 s15, 0
	s_nop 0
.Lattn_loop:
	s_barrier
	s_waitcnt lgkmcnt(3)
	v_mfma_f32_16x16x32_bf16 v[114:117], v[178:181], v[146:149], v[2:5]
	v_add_f32_e32 v250, v82, v250
	s_add_u32 s98, s98, 0x8000
	s_addc_u32 s99, s99, 0
	s_add_u32 s100, s100, 0x8000
	s_addc_u32 s101, s101, 0
	v_mfma_f32_16x16x32_bf16 v[118:121], v[178:181], v[162:165], v[2:5]
	ds_read_b128 v[178:181], v235 offset:16384
	v_add_f32_e32 v250, v83, v250
	v_add_f32_e32 v250, v84, v250
	s_waitcnt lgkmcnt(3)
	v_mfma_f32_16x16x32_bf16 v[122:125], v[182:185], v[146:149], v[2:5]
	v_add_f32_e32 v250, v85, v250
	s_add_u32 m0, s79, 0
	s_nop 0
	global_load_lds_dwordx4 v246, s[98:99]
	v_mfma_f32_16x16x32_bf16 v[126:129], v[182:185], v[162:165], v[2:5]
	ds_read_b128 v[182:185], v235 offset:20480
	v_add_f32_e32 v250, v90, v250
	v_add_f32_e32 v250, v91, v250
	s_waitcnt lgkmcnt(3)
	v_mfma_f32_16x16x32_bf16 v[130:133], v[186:189], v[146:149], v[2:5]
	v_add_f32_e32 v250, v92, v250
	v_mfma_f32_16x16x32_bf16 v[134:137], v[186:189], v[162:165], v[2:5]
	ds_read_b128 v[186:189], v235 offset:24576
	v_add_f32_e32 v250, v93, v250
	v_cvt_pk_bf16_f32 v82, v82, v83
	s_waitcnt lgkmcnt(3)
	v_mfma_f32_16x16x32_bf16 v[138:141], v[190:193], v[146:149], v[2:5]
	v_cvt_pk_bf16_f32 v83, v84, v85
	s_add_u32 m0, s79, 1024
	s_nop 0
	global_load_lds_dwordx4 v247, s[98:99]
	v_mfma_f32_16x16x32_bf16 v[142:145], v[190:193], v[162:165], v[2:5]
	ds_read_b128 v[190:193], v235 offset:28672
	v_cvt_pk_bf16_f32 v84, v90, v91
	v_cvt_pk_bf16_f32 v85, v92, v93
	s_waitcnt lgkmcnt(3)
	v_mfma_f32_16x16x32_bf16 v[114:117], v[178:181], v[150:153], v[114:117]
	v_add_f32_e32 v251, v86, v251
	v_mfma_f32_16x16x32_bf16 v[118:121], v[178:181], v[166:169], v[118:121]
	ds_read_b128 v[178:181], v236 offset:16384
	v_add_f32_e32 v251, v87, v251
	v_add_f32_e32 v251, v88, v251
	s_waitcnt lgkmcnt(3)
	v_mfma_f32_16x16x32_bf16 v[122:125], v[182:185], v[150:153], v[122:125]
	v_add_f32_e32 v251, v89, v251
	s_add_u32 m0, s80, 49152
	s_nop 0
	global_load_lds_dwordx4 v248, s[100:101]
	v_mfma_f32_16x16x32_bf16 v[126:129], v[182:185], v[166:169], v[126:129]
	ds_read_b128 v[182:185], v236 offset:20480
	v_add_f32_e32 v251, v94, v251
	v_add_f32_e32 v251, v95, v251
	s_waitcnt lgkmcnt(3)
	v_mfma_f32_16x16x32_bf16 v[130:133], v[186:189], v[150:153], v[130:133]
	v_add_f32_e32 v251, v96, v251
	v_mfma_f32_16x16x32_bf16 v[134:137], v[186:189], v[166:169], v[134:137]
	ds_read_b128 v[186:189], v236 offset:24576
	v_add_f32_e32 v251, v97, v251
	v_cvt_pk_bf16_f32 v86, v86, v87
	s_waitcnt lgkmcnt(3)
	v_mfma_f32_16x16x32_bf16 v[138:141], v[190:193], v[150:153], v[138:141]
	v_cvt_pk_bf16_f32 v87, v88, v89
	s_add_u32 m0, s80, 50176
	s_nop 0
	global_load_lds_dwordx4 v249, s[100:101]
	v_mfma_f32_16x16x32_bf16 v[142:145], v[190:193], v[166:169], v[142:145]
	ds_read_b128 v[190:193], v236 offset:28672
	v_cvt_pk_bf16_f32 v88, v94, v95
	v_cvt_pk_bf16_f32 v89, v96, v97
	s_waitcnt lgkmcnt(3)
	v_mfma_f32_16x16x32_bf16 v[114:117], v[178:181], v[154:157], v[114:117]
	v_add_f32_e32 v250, v98, v250
	v_mfma_f32_16x16x32_bf16 v[118:121], v[178:181], v[170:173], v[118:121]
	ds_read_b128 v[178:181], v237 offset:16384
	v_add_f32_e32 v250, v99, v250
	v_add_f32_e32 v250, v100, v250
	s_waitcnt lgkmcnt(3)
	v_mfma_f32_16x16x32_bf16 v[122:125], v[182:185], v[154:157], v[122:125]
	v_add_f32_e32 v250, v101, v250
	v_mfma_f32_16x16x32_bf16 v[126:129], v[182:185], v[170:173], v[126:129]
	ds_read_b128 v[182:185], v237 offset:20480
	v_add_f32_e32 v250, v106, v250
	v_add_f32_e32 v250, v107, v250
	s_waitcnt lgkmcnt(3)
	v_mfma_f32_16x16x32_bf16 v[130:133], v[186:189], v[154:157], v[130:133]
	v_add_f32_e32 v250, v108, v250
	ds_read_b64_tr_b16 v[202:203], v238 offset:0
	ds_read_b64_tr_b16 v[204:205], v238 offset:4096
	v_mfma_f32_16x16x32_bf16 v[134:137], v[186:189], v[170:173], v[134:137]
	ds_read_b128 v[186:189], v237 offset:24576
	v_add_f32_e32 v250, v109, v250
	v_cvt_pk_bf16_f32 v98, v98, v99
	s_waitcnt lgkmcnt(5)
	v_mfma_f32_16x16x32_bf16 v[138:141], v[190:193], v[154:157], v[138:141]
	v_cvt_pk_bf16_f32 v99, v100, v101
	ds_read_b64_tr_b16 v[206:207], v239 offset:0
	ds_read_b64_tr_b16 v[208:209], v239 offset:4096
	v_mfma_f32_16x16x32_bf16 v[142:145], v[190:193], v[170:173], v[142:145]
	ds_read_b128 v[190:193], v237 offset:28672
	v_cvt_pk_bf16_f32 v100, v106, v107
	v_cvt_pk_bf16_f32 v101, v108, v109
	s_waitcnt lgkmcnt(7)
	v_mfma_f32_16x16x32_bf16 v[114:117], v[178:181], v[158:161], v[114:117]
	v_add_f32_e32 v251, v102, v251
	ds_read_b64_tr_b16 v[210:211], v240 offset:0
	ds_read_b64_tr_b16 v[212:213], v240 offset:4096
	v_mfma_f32_16x16x32_bf16 v[118:121], v[178:181], v[174:177], v[118:121]
	v_add_f32_e32 v251, v103, v251
	v_add_f32_e32 v251, v104, v251
	s_waitcnt lgkmcnt(8)
	v_mfma_f32_16x16x32_bf16 v[122:125], v[182:185], v[158:161], v[122:125]
	v_add_f32_e32 v251, v105, v251
	ds_read_b64_tr_b16 v[214:215], v241 offset:0
	ds_read_b64_tr_b16 v[216:217], v241 offset:4096
	v_mfma_f32_16x16x32_bf16 v[126:129], v[182:185], v[174:177], v[126:129]
	v_add_f32_e32 v251, v110, v251
	v_add_f32_e32 v251, v111, v251
	s_waitcnt lgkmcnt(7)
	v_mfma_f32_16x16x32_bf16 v[130:133], v[186:189], v[158:161], v[130:133]
	v_add_f32_e32 v251, v112, v251
	ds_read_b64_tr_b16 v[218:219], v242 offset:0
	ds_read_b64_tr_b16 v[220:221], v242 offset:4096
	v_mfma_f32_16x16x32_bf16 v[134:137], v[186:189], v[174:177], v[134:137]
	v_add_f32_e32 v251, v113, v251
	v_cvt_pk_bf16_f32 v102, v102, v103
	s_waitcnt lgkmcnt(6)
; #define SBAR() __builtin_amdgcn_sched_barrier(0)
; #define SLOAD(i, k0) do { sr_[i].vs0 = St::ld8(&Vh[(long)((k0) + sr) * LDK + sc]); sr_[i].vs1 = St::ld8(&Vh[(long)((k0) + 32 + sr) * LDK + sc]); \
;     sr_[i].ks0 = St::ld8(&Kh[(long)((k0) + sr) * LDK + sc]); sr_[i].ks1 = St::ld8(&Kh[(long)((k0) + 32 + sr) * LDK + sc]); } while (0)
; #define SWAIT() do { if constexpr (SDEPTH == 2) asm volatile("s_waitcnt vmcnt(4)" ::: "memory"); else asm volatile("s_waitcnt vmcnt(0)" ::: "memory"); } while (0)
; template <typename TQ> ...
;     ...
;   for (int j = 1; j + 1 < NT; j += 2) {
;     SBAR(); SLOAD(SO, (j + SDEPTH) * KVBLK); SBAR();
;     qkt(pB0, pB1, (bf16*)((char*)K_lds + SHM_K), qr, r32, hi, negm);
;     finishSM(pA0, pA1, l_reg, pa0, pa1, pa2, pa3); SBAR();
;     pv_d0(o, vb0, pa0, pa1, pa2, pa3); partialSM(pB0, pB1, mC);
;     __syncthreads(); SWAIT(); SWRITE(0, SE);
;     __syncthreads();
;     SBAR(); if (SDEPTH == 1 || j + 3 < NT) SLOAD(SE, (j + 1 + SDEPTH) * KVBLK); SBAR();
;     qkt(pA0, pA1, K_lds, qr, r32, hi, negm);
;     finishSM(pB0, pB1, l_reg, pa0, pa1, pa2, pa3); SBAR();
;     pv_d0(o, vb0 + (int)SHM_V, pa0, pa1, pa2, pa3); partialSM(pA0, pA1, mC);
;     __syncthreads(); SWAIT(); SWRITE(1, SO);
;     __syncthreads();
;   }
	v_mfma_f32_16x16x32_bf16 v[138:141], v[190:193], v[158:161], v[138:141]
	v_cvt_pk_bf16_f32 v103, v104, v105
	ds_read_b64_tr_b16 v[222:223], v243 offset:0
	ds_read_b64_tr_b16 v[224:225], v243 offset:4096
	v_mfma_f32_16x16x32_bf16 v[142:145], v[190:193], v[174:177], v[142:145]
	v_cvt_pk_bf16_f32 v104, v110, v111
	v_cvt_pk_bf16_f32 v105, v112, v113
	v_mfma_f32_16x16x32_bf16 v[18:21], v[202:205], v[82:85], v[18:21]
	v_exp_f32_e32 v114, v114
	v_mfma_f32_16x16x32_bf16 v[22:25], v[202:205], v[86:89], v[22:25]
	ds_read_b64_tr_b16 v[202:203], v244 offset:0
	ds_read_b64_tr_b16 v[204:205], v244 offset:4096
	v_exp_f32_e32 v115, v115
	v_mfma_f32_16x16x32_bf16 v[26:29], v[206:209], v[82:85], v[26:29]
	v_exp_f32_e32 v116, v116
	v_mfma_f32_16x16x32_bf16 v[30:33], v[206:209], v[86:89], v[30:33]
	ds_read_b64_tr_b16 v[206:207], v245 offset:0
	ds_read_b64_tr_b16 v[208:209], v245 offset:4096
	v_exp_f32_e32 v117, v117
	s_waitcnt lgkmcnt(10)
	v_mfma_f32_16x16x32_bf16 v[34:37], v[210:213], v[82:85], v[34:37]
	v_exp_f32_e32 v118, v118
	v_mfma_f32_16x16x32_bf16 v[38:41], v[210:213], v[86:89], v[38:41]
	ds_read_b64_tr_b16 v[210:211], v238 offset:8192
	ds_read_b64_tr_b16 v[212:213], v238 offset:12288
	v_exp_f32_e32 v119, v119
	s_waitcnt lgkmcnt(10)
	v_mfma_f32_16x16x32_bf16 v[42:45], v[214:217], v[82:85], v[42:45]
	v_exp_f32_e32 v120, v120
	v_mfma_f32_16x16x32_bf16 v[46:49], v[214:217], v[86:89], v[46:49]
	ds_read_b64_tr_b16 v[214:215], v239 offset:8192
	ds_read_b64_tr_b16 v[216:217], v239 offset:12288
	v_exp_f32_e32 v121, v121
	s_waitcnt lgkmcnt(10)
	v_mfma_f32_16x16x32_bf16 v[50:53], v[218:221], v[82:85], v[50:53]
	v_exp_f32_e32 v122, v122
	v_mfma_f32_16x16x32_bf16 v[54:57], v[218:221], v[86:89], v[54:57]
	ds_read_b64_tr_b16 v[218:219], v240 offset:8192
	ds_read_b64_tr_b16 v[220:221], v240 offset:12288
	v_exp_f32_e32 v123, v123
	s_waitcnt lgkmcnt(10)
	v_mfma_f32_16x16x32_bf16 v[58:61], v[222:225], v[82:85], v[58:61]
	v_exp_f32_e32 v124, v124
	v_mfma_f32_16x16x32_bf16 v[62:65], v[222:225], v[86:89], v[62:65]
	ds_read_b64_tr_b16 v[222:223], v241 offset:8192
	ds_read_b64_tr_b16 v[224:225], v241 offset:12288
	v_exp_f32_e32 v125, v125
	s_waitcnt lgkmcnt(10)
	v_mfma_f32_16x16x32_bf16 v[66:69], v[202:205], v[82:85], v[66:69]
	v_exp_f32_e32 v126, v126
	v_mfma_f32_16x16x32_bf16 v[70:73], v[202:205], v[86:89], v[70:73]
	ds_read_b64_tr_b16 v[202:203], v242 offset:8192
	ds_read_b64_tr_b16 v[204:205], v242 offset:12288
	v_exp_f32_e32 v127, v127
	s_waitcnt lgkmcnt(10)
	v_mfma_f32_16x16x32_bf16 v[74:77], v[206:209], v[82:85], v[74:77]
	v_exp_f32_e32 v128, v128
	v_mfma_f32_16x16x32_bf16 v[78:81], v[206:209], v[86:89], v[78:81]
	ds_read_b64_tr_b16 v[206:207], v243 offset:8192
	ds_read_b64_tr_b16 v[208:209], v243 offset:12288
	v_exp_f32_e32 v129, v129
	s_waitcnt lgkmcnt(10)
	v_mfma_f32_16x16x32_bf16 v[18:21], v[210:213], v[98:101], v[18:21]
	v_exp_f32_e32 v130, v130
	v_mfma_f32_16x16x32_bf16 v[22:25], v[210:213], v[102:105], v[22:25]
	ds_read_b64_tr_b16 v[210:211], v244 offset:8192
	ds_read_b64_tr_b16 v[212:213], v244 offset:12288
	v_exp_f32_e32 v131, v131
	s_waitcnt lgkmcnt(10)
	v_mfma_f32_16x16x32_bf16 v[26:29], v[214:217], v[98:101], v[26:29]
	v_exp_f32_e32 v132, v132
	v_mfma_f32_16x16x32_bf16 v[30:33], v[214:217], v[102:105], v[30:33]
	ds_read_b64_tr_b16 v[214:215], v245 offset:8192
	ds_read_b64_tr_b16 v[216:217], v245 offset:12288
	v_exp_f32_e32 v133, v133
	s_waitcnt lgkmcnt(10)
	v_mfma_f32_16x16x32_bf16 v[34:37], v[218:221], v[98:101], v[34:37]
	v_exp_f32_e32 v134, v134
	v_mfma_f32_16x16x32_bf16 v[38:41], v[218:221], v[102:105], v[38:41]
	v_exp_f32_e32 v135, v135
	s_waitcnt lgkmcnt(8)
	v_mfma_f32_16x16x32_bf16 v[42:45], v[222:225], v[98:101], v[42:45]
	v_exp_f32_e32 v136, v136
	v_mfma_f32_16x16x32_bf16 v[46:49], v[222:225], v[102:105], v[46:49]
	v_exp_f32_e32 v137, v137
	s_waitcnt lgkmcnt(6)
	v_mfma_f32_16x16x32_bf16 v[50:53], v[202:205], v[98:101], v[50:53]
	v_exp_f32_e32 v138, v138
	ds_read_b128 v[178:181], v234 offset:32768
	v_mfma_f32_16x16x32_bf16 v[54:57], v[202:205], v[102:105], v[54:57]
	v_exp_f32_e32 v139, v139
	s_waitcnt lgkmcnt(5)
	v_mfma_f32_16x16x32_bf16 v[58:61], v[206:209], v[98:101], v[58:61]
	v_exp_f32_e32 v140, v140
	ds_read_b128 v[182:185], v234 offset:36864
	v_mfma_f32_16x16x32_bf16 v[62:65], v[206:209], v[102:105], v[62:65]
	v_exp_f32_e32 v141, v141
	s_waitcnt lgkmcnt(4)
	v_mfma_f32_16x16x32_bf16 v[66:69], v[210:213], v[98:101], v[66:69]
	v_exp_f32_e32 v142, v142
	ds_read_b128 v[186:189], v234 offset:40960
	v_mfma_f32_16x16x32_bf16 v[70:73], v[210:213], v[102:105], v[70:73]
	v_exp_f32_e32 v143, v143
	s_waitcnt lgkmcnt(3)
	v_mfma_f32_16x16x32_bf16 v[74:77], v[214:217], v[98:101], v[74:77]
	v_exp_f32_e32 v144, v144
	ds_read_b128 v[190:193], v234 offset:45056
	v_mfma_f32_16x16x32_bf16 v[78:81], v[214:217], v[102:105], v[78:81]
	v_exp_f32_e32 v145, v145
	s_waitcnt vmcnt(4)
	s_barrier
; #define SBAR() __builtin_amdgcn_sched_barrier(0)
; #define SLOAD(i, k0) do { sr_[i].vs0 = St::ld8(&Vh[(long)((k0) + sr) * LDK + sc]); sr_[i].vs1 = St::ld8(&Vh[(long)((k0) + 32 + sr) * LDK + sc]); \
;     sr_[i].ks0 = St::ld8(&Kh[(long)((k0) + sr) * LDK + sc]); sr_[i].ks1 = St::ld8(&Kh[(long)((k0) + 32 + sr) * LDK + sc]); } while (0)
; #define SWAIT() do { if constexpr (SDEPTH == 2) asm volatile("s_waitcnt vmcnt(4)" ::: "memory"); else asm volatile("s_waitcnt vmcnt(0)" ::: "memory"); } while (0)
; template <typename TQ> ...
;     ...
;   for (int j = 1; j + 1 < NT; j += 2) {
;     SBAR(); SLOAD(SO, (j + SDEPTH) * KVBLK); SBAR();
;     qkt(pB0, pB1, (bf16*)((char*)K_lds + SHM_K), qr, r32, hi, negm);
;     finishSM(pA0, pA1, l_reg, pa0, pa1, pa2, pa3); SBAR();
;     pv_d0(o, vb0, pa0, pa1, pa2, pa3); partialSM(pB0, pB1, mC);
;     __syncthreads(); SWAIT(); SWRITE(0, SE);
;     __syncthreads();
;     SBAR(); if (SDEPTH == 1 || j + 3 < NT) SLOAD(SE, (j + 1 + SDEPTH) * KVBLK); SBAR();
;     qkt(pA0, pA1, K_lds, qr, r32, hi, negm);
;     finishSM(pB0, pB1, l_reg, pa0, pa1, pa2, pa3); SBAR();
;     pv_d0(o, vb0 + (int)SHM_V, pa0, pa1, pa2, pa3); partialSM(pA0, pA1, mC);
;     __syncthreads(); SWAIT(); SWRITE(1, SO);
;     __syncthreads();
;   }
	s_waitcnt lgkmcnt(3)
	v_mfma_f32_16x16x32_bf16 v[82:85], v[178:181], v[146:149], v[2:5]
	v_add_f32_e32 v250, v114, v250
	s_add_u32 s98, s98, 0x8000
	s_addc_u32 s99, s99, 0
	s_add_u32 s100, s100, 0x8000
	s_addc_u32 s101, s101, 0
	v_mfma_f32_16x16x32_bf16 v[86:89], v[178:181], v[162:165], v[2:5]
	ds_read_b128 v[178:181], v235 offset:32768
	v_add_f32_e32 v250, v115, v250
	v_add_f32_e32 v250, v116, v250
	s_waitcnt lgkmcnt(3)
	v_mfma_f32_16x16x32_bf16 v[90:93], v[182:185], v[146:149], v[2:5]
	v_add_f32_e32 v250, v117, v250
	s_add_u32 m0, s79, 16384
	s_nop 0
	global_load_lds_dwordx4 v246, s[98:99]
	v_mfma_f32_16x16x32_bf16 v[94:97], v[182:185], v[162:165], v[2:5]
	ds_read_b128 v[182:185], v235 offset:36864
	v_add_f32_e32 v250, v122, v250
	v_add_f32_e32 v250, v123, v250
	s_waitcnt lgkmcnt(3)
	v_mfma_f32_16x16x32_bf16 v[98:101], v[186:189], v[146:149], v[2:5]
	v_add_f32_e32 v250, v124, v250
	v_mfma_f32_16x16x32_bf16 v[102:105], v[186:189], v[162:165], v[2:5]
	ds_read_b128 v[186:189], v235 offset:40960
	v_add_f32_e32 v250, v125, v250
	v_cvt_pk_bf16_f32 v114, v114, v115
	s_waitcnt lgkmcnt(3)
	v_mfma_f32_16x16x32_bf16 v[106:109], v[190:193], v[146:149], v[2:5]
	v_cvt_pk_bf16_f32 v115, v116, v117
	s_add_u32 m0, s79, 17408
	s_nop 0
	global_load_lds_dwordx4 v247, s[98:99]
	v_mfma_f32_16x16x32_bf16 v[110:113], v[190:193], v[162:165], v[2:5]
	ds_read_b128 v[190:193], v235 offset:45056
	v_cvt_pk_bf16_f32 v116, v122, v123
	v_cvt_pk_bf16_f32 v117, v124, v125
	s_waitcnt lgkmcnt(3)
	v_mfma_f32_16x16x32_bf16 v[82:85], v[178:181], v[150:153], v[82:85]
	v_add_f32_e32 v251, v118, v251
	v_mfma_f32_16x16x32_bf16 v[86:89], v[178:181], v[166:169], v[86:89]
	ds_read_b128 v[178:181], v236 offset:32768
	v_add_f32_e32 v251, v119, v251
	v_add_f32_e32 v251, v120, v251
	s_waitcnt lgkmcnt(3)
	v_mfma_f32_16x16x32_bf16 v[90:93], v[182:185], v[150:153], v[90:93]
	v_add_f32_e32 v251, v121, v251
	s_add_u32 m0, s80, 0
	s_nop 0
	global_load_lds_dwordx4 v248, s[100:101]
	v_mfma_f32_16x16x32_bf16 v[94:97], v[182:185], v[166:169], v[94:97]
	ds_read_b128 v[182:185], v236 offset:36864
	v_add_f32_e32 v251, v126, v251
	v_add_f32_e32 v251, v127, v251
	s_waitcnt lgkmcnt(3)
	v_mfma_f32_16x16x32_bf16 v[98:101], v[186:189], v[150:153], v[98:101]
	v_add_f32_e32 v251, v128, v251
	v_mfma_f32_16x16x32_bf16 v[102:105], v[186:189], v[166:169], v[102:105]
	ds_read_b128 v[186:189], v236 offset:40960
	v_add_f32_e32 v251, v129, v251
	v_cvt_pk_bf16_f32 v118, v118, v119
	s_waitcnt lgkmcnt(3)
	v_mfma_f32_16x16x32_bf16 v[106:109], v[190:193], v[150:153], v[106:109]
	v_cvt_pk_bf16_f32 v119, v120, v121
	s_add_u32 m0, s80, 1024
	s_nop 0
	global_load_lds_dwordx4 v249, s[100:101]
	v_mfma_f32_16x16x32_bf16 v[110:113], v[190:193], v[166:169], v[110:113]
	ds_read_b128 v[190:193], v236 offset:45056
	v_cvt_pk_bf16_f32 v120, v126, v127
	v_cvt_pk_bf16_f32 v121, v128, v129
	s_waitcnt lgkmcnt(3)
	v_mfma_f32_16x16x32_bf16 v[82:85], v[178:181], v[154:157], v[82:85]
	v_add_f32_e32 v250, v130, v250
	v_mfma_f32_16x16x32_bf16 v[86:89], v[178:181], v[170:173], v[86:89]
	ds_read_b128 v[178:181], v237 offset:32768
	v_add_f32_e32 v250, v131, v250
	v_add_f32_e32 v250, v132, v250
	s_waitcnt lgkmcnt(3)
	v_mfma_f32_16x16x32_bf16 v[90:93], v[182:185], v[154:157], v[90:93]
	v_add_f32_e32 v250, v133, v250
	v_mfma_f32_16x16x32_bf16 v[94:97], v[182:185], v[170:173], v[94:97]
	ds_read_b128 v[182:185], v237 offset:36864
	v_add_f32_e32 v250, v138, v250
	v_add_f32_e32 v250, v139, v250
	s_waitcnt lgkmcnt(3)
	v_mfma_f32_16x16x32_bf16 v[98:101], v[186:189], v[154:157], v[98:101]
	v_add_f32_e32 v250, v140, v250
	ds_read_b64_tr_b16 v[202:203], v238 offset:16384
	ds_read_b64_tr_b16 v[204:205], v238 offset:20480
	v_mfma_f32_16x16x32_bf16 v[102:105], v[186:189], v[170:173], v[102:105]
	ds_read_b128 v[186:189], v237 offset:40960
	v_add_f32_e32 v250, v141, v250
	v_cvt_pk_bf16_f32 v130, v130, v131
	s_waitcnt lgkmcnt(5)
	v_mfma_f32_16x16x32_bf16 v[106:109], v[190:193], v[154:157], v[106:109]
	v_cvt_pk_bf16_f32 v131, v132, v133
	ds_read_b64_tr_b16 v[206:207], v239 offset:16384
	ds_read_b64_tr_b16 v[208:209], v239 offset:20480
	v_mfma_f32_16x16x32_bf16 v[110:113], v[190:193], v[170:173], v[110:113]
	ds_read_b128 v[190:193], v237 offset:45056
	v_cvt_pk_bf16_f32 v132, v138, v139
	v_cvt_pk_bf16_f32 v133, v140, v141
	s_waitcnt lgkmcnt(7)
	v_mfma_f32_16x16x32_bf16 v[82:85], v[178:181], v[158:161], v[82:85]
	v_add_f32_e32 v251, v134, v251
	ds_read_b64_tr_b16 v[210:211], v240 offset:16384
	ds_read_b64_tr_b16 v[212:213], v240 offset:20480
	v_mfma_f32_16x16x32_bf16 v[86:89], v[178:181], v[174:177], v[86:89]
	v_add_f32_e32 v251, v135, v251
	v_add_f32_e32 v251, v136, v251
	s_waitcnt lgkmcnt(8)
	v_mfma_f32_16x16x32_bf16 v[90:93], v[182:185], v[158:161], v[90:93]
	v_add_f32_e32 v251, v137, v251
	ds_read_b64_tr_b16 v[214:215], v241 offset:16384
	ds_read_b64_tr_b16 v[216:217], v241 offset:20480
	v_mfma_f32_16x16x32_bf16 v[94:97], v[182:185], v[174:177], v[94:97]
	v_add_f32_e32 v251, v142, v251
	v_add_f32_e32 v251, v143, v251
	s_waitcnt lgkmcnt(7)
	v_mfma_f32_16x16x32_bf16 v[98:101], v[186:189], v[158:161], v[98:101]
	v_add_f32_e32 v251, v144, v251
	ds_read_b64_tr_b16 v[218:219], v242 offset:16384
	ds_read_b64_tr_b16 v[220:221], v242 offset:20480
	v_mfma_f32_16x16x32_bf16 v[102:105], v[186:189], v[174:177], v[102:105]
	v_add_f32_e32 v251, v145, v251
	v_cvt_pk_bf16_f32 v134, v134, v135
	s_waitcnt lgkmcnt(6)
; #define SBAR() __builtin_amdgcn_sched_barrier(0)
; __device__ __forceinline__ void partialSM(f32x16& p0, f32x16& p1, float mC) {
;   (void)mC; (void)p1;
;   for (int r = 0; r < 16; ++r) p0[r] = __builtin_amdgcn_exp2f(p0[r]);
; }
; __device__ __forceinline__ void finishSM(f32x16& p0, f32x16& p1, float& l_reg, bf16x8& pa0, bf16x8& pa1, bf16x8& pa2, bf16x8& pa3) {
;   for (int r = 0; r < 16; ++r) p1[r] = __builtin_amdgcn_exp2f(p1[r]);
; template <int D0> __device__ __forceinline__ void pv_one(f32x16& od, int vb, bf16x8 pa0, bf16x8 pa1, bf16x8 pa2, bf16x8 pa3) {
;   const s16x4 l0 = tr_read<v_rd_off(D0, 0, 0)>(vb), h0 = tr_read<v_rd_off(D0, 0, 1)>(vb), l1 = tr_read<v_rd_off(D0, 1, 0)>(vb), h1 = tr_read<v_rd_off(D0, 1, 1)>(vb);
;   const s16x4 l2 = tr_read<v_rd_off(D0, 2, 0)>(vb), h2 = tr_read<v_rd_off(D0, 2, 1)>(vb), l3 = tr_read<v_rd_off(D0, 3, 0)>(vb), h3 = tr_read<v_rd_off(D0, 3, 1)>(vb);
;   asm volatile("s_waitcnt lgkmcnt(0)" ::: "memory"); SBAR();
;     ...
;   od = __builtin_amdgcn_mfma_f32_32x32x16_bf16(pa0, PK(l0, h0), od, 0, 0, 0);
;   od = __builtin_amdgcn_mfma_f32_32x32x16_bf16(pa1, PK(l1, h1), od, 0, 0, 0);
;   od = __builtin_amdgcn_mfma_f32_32x32x16_bf16(pa2, PK(l2, h2), od, 0, 0, 0);
;   od = __builtin_amdgcn_mfma_f32_32x32x16_bf16(pa3, PK(l3, h3), od, 0, 0, 0);
;     ...
; }
; __device__ __forceinline__ void pv_d0(f32x16* o, int vb, bf16x8 pa0, bf16x8 pa1, bf16x8 pa2, bf16x8 pa3) {
;   pv_one<0>(o[0], vb, pa0, pa1, pa2, pa3); pv_one<1>(o[1], vb, pa0, pa1, pa2, pa3); pv_one<2>(o[2], vb, pa0, pa1, pa2, pa3); pv_one<3>(o[3], vb, pa0, pa1, pa2, pa3);
	v_mfma_f32_16x16x32_bf16 v[106:109], v[190:193], v[158:161], v[106:109]
	v_cvt_pk_bf16_f32 v135, v136, v137
	ds_read_b64_tr_b16 v[222:223], v243 offset:16384
	ds_read_b64_tr_b16 v[224:225], v243 offset:20480
	v_mfma_f32_16x16x32_bf16 v[110:113], v[190:193], v[174:177], v[110:113]
	v_cvt_pk_bf16_f32 v136, v142, v143
	v_cvt_pk_bf16_f32 v137, v144, v145
	v_mfma_f32_16x16x32_bf16 v[18:21], v[202:205], v[114:117], v[18:21]
	v_exp_f32_e32 v82, v82
	v_mfma_f32_16x16x32_bf16 v[22:25], v[202:205], v[118:121], v[22:25]
	ds_read_b64_tr_b16 v[202:203], v244 offset:16384
	ds_read_b64_tr_b16 v[204:205], v244 offset:20480
	v_exp_f32_e32 v83, v83
	v_mfma_f32_16x16x32_bf16 v[26:29], v[206:209], v[114:117], v[26:29]
	v_exp_f32_e32 v84, v84
	v_mfma_f32_16x16x32_bf16 v[30:33], v[206:209], v[118:121], v[30:33]
	ds_read_b64_tr_b16 v[206:207], v245 offset:16384
	ds_read_b64_tr_b16 v[208:209], v245 offset:20480
	v_exp_f32_e32 v85, v85
	s_waitcnt lgkmcnt(10)
	v_mfma_f32_16x16x32_bf16 v[34:37], v[210:213], v[114:117], v[34:37]
	v_exp_f32_e32 v86, v86
	v_mfma_f32_16x16x32_bf16 v[38:41], v[210:213], v[118:121], v[38:41]
	ds_read_b64_tr_b16 v[210:211], v238 offset:24576
	ds_read_b64_tr_b16 v[212:213], v238 offset:28672
	v_exp_f32_e32 v87, v87
	s_waitcnt lgkmcnt(10)
	v_mfma_f32_16x16x32_bf16 v[42:45], v[214:217], v[114:117], v[42:45]
	v_exp_f32_e32 v88, v88
	v_mfma_f32_16x16x32_bf16 v[46:49], v[214:217], v[118:121], v[46:49]
	ds_read_b64_tr_b16 v[214:215], v239 offset:24576
	ds_read_b64_tr_b16 v[216:217], v239 offset:28672
	v_exp_f32_e32 v89, v89
	s_waitcnt lgkmcnt(10)
	v_mfma_f32_16x16x32_bf16 v[50:53], v[218:221], v[114:117], v[50:53]
	v_exp_f32_e32 v90, v90
	v_mfma_f32_16x16x32_bf16 v[54:57], v[218:221], v[118:121], v[54:57]
	ds_read_b64_tr_b16 v[218:219], v240 offset:24576
	ds_read_b64_tr_b16 v[220:221], v240 offset:28672
	v_exp_f32_e32 v91, v91
	s_waitcnt lgkmcnt(10)
	v_mfma_f32_16x16x32_bf16 v[58:61], v[222:225], v[114:117], v[58:61]
	v_exp_f32_e32 v92, v92
	v_mfma_f32_16x16x32_bf16 v[62:65], v[222:225], v[118:121], v[62:65]
	ds_read_b64_tr_b16 v[222:223], v241 offset:24576
	ds_read_b64_tr_b16 v[224:225], v241 offset:28672
	v_exp_f32_e32 v93, v93
	s_waitcnt lgkmcnt(10)
	v_mfma_f32_16x16x32_bf16 v[66:69], v[202:205], v[114:117], v[66:69]
	v_exp_f32_e32 v94, v94
	v_mfma_f32_16x16x32_bf16 v[70:73], v[202:205], v[118:121], v[70:73]
	ds_read_b64_tr_b16 v[202:203], v242 offset:24576
	ds_read_b64_tr_b16 v[204:205], v242 offset:28672
	v_exp_f32_e32 v95, v95
	s_waitcnt lgkmcnt(10)
	v_mfma_f32_16x16x32_bf16 v[74:77], v[206:209], v[114:117], v[74:77]
	v_exp_f32_e32 v96, v96
	v_mfma_f32_16x16x32_bf16 v[78:81], v[206:209], v[118:121], v[78:81]
	ds_read_b64_tr_b16 v[206:207], v243 offset:24576
	ds_read_b64_tr_b16 v[208:209], v243 offset:28672
	v_exp_f32_e32 v97, v97
	s_waitcnt lgkmcnt(10)
	v_mfma_f32_16x16x32_bf16 v[18:21], v[210:213], v[130:133], v[18:21]
	v_exp_f32_e32 v98, v98
	v_mfma_f32_16x16x32_bf16 v[22:25], v[210:213], v[134:137], v[22:25]
	ds_read_b64_tr_b16 v[210:211], v244 offset:24576
	ds_read_b64_tr_b16 v[212:213], v244 offset:28672
	v_exp_f32_e32 v99, v99
	s_waitcnt lgkmcnt(10)
	v_mfma_f32_16x16x32_bf16 v[26:29], v[214:217], v[130:133], v[26:29]
	v_exp_f32_e32 v100, v100
	v_mfma_f32_16x16x32_bf16 v[30:33], v[214:217], v[134:137], v[30:33]
	ds_read_b64_tr_b16 v[214:215], v245 offset:24576
	ds_read_b64_tr_b16 v[216:217], v245 offset:28672
	v_exp_f32_e32 v101, v101
	s_waitcnt lgkmcnt(10)
	v_mfma_f32_16x16x32_bf16 v[34:37], v[218:221], v[130:133], v[34:37]
	v_exp_f32_e32 v102, v102
	v_mfma_f32_16x16x32_bf16 v[38:41], v[218:221], v[134:137], v[38:41]
	v_exp_f32_e32 v103, v103
	s_waitcnt lgkmcnt(8)
	v_mfma_f32_16x16x32_bf16 v[42:45], v[222:225], v[130:133], v[42:45]
	v_exp_f32_e32 v104, v104
	v_mfma_f32_16x16x32_bf16 v[46:49], v[222:225], v[134:137], v[46:49]
	v_exp_f32_e32 v105, v105
	s_waitcnt lgkmcnt(6)
	v_mfma_f32_16x16x32_bf16 v[50:53], v[202:205], v[130:133], v[50:53]
	v_exp_f32_e32 v106, v106
	ds_read_b128 v[178:181], v234 offset:49152
	v_mfma_f32_16x16x32_bf16 v[54:57], v[202:205], v[134:137], v[54:57]
	v_exp_f32_e32 v107, v107
	s_waitcnt lgkmcnt(5)
	v_mfma_f32_16x16x32_bf16 v[58:61], v[206:209], v[130:133], v[58:61]
	v_exp_f32_e32 v108, v108
	ds_read_b128 v[182:185], v234 offset:53248
	v_mfma_f32_16x16x32_bf16 v[62:65], v[206:209], v[134:137], v[62:65]
	v_exp_f32_e32 v109, v109
	s_waitcnt lgkmcnt(4)
	v_mfma_f32_16x16x32_bf16 v[66:69], v[210:213], v[130:133], v[66:69]
	v_exp_f32_e32 v110, v110
	ds_read_b128 v[186:189], v234 offset:57344
	v_mfma_f32_16x16x32_bf16 v[70:73], v[210:213], v[134:137], v[70:73]
	v_exp_f32_e32 v111, v111
	s_waitcnt lgkmcnt(3)
	v_mfma_f32_16x16x32_bf16 v[74:77], v[214:217], v[130:133], v[74:77]
	v_exp_f32_e32 v112, v112
	ds_read_b128 v[190:193], v234 offset:61440
	v_mfma_f32_16x16x32_bf16 v[78:81], v[214:217], v[134:137], v[78:81]
	v_exp_f32_e32 v113, v113
	s_waitcnt vmcnt(4)
	s_barrier
; __device__ __forceinline__ void finishSM(f32x16& p0, f32x16& p1, float& l_reg, bf16x8& pa0, bf16x8& pa1, bf16x8& pa2, bf16x8& pa3) {
;   for (int r = 0; r < 16; ++r) p1[r] = __builtin_amdgcn_exp2f(p1[r]);
;   float ps = 0; for (int r = 0; r < 16; ++r) ps += p0[r]; for (int r = 0; r < 16; ++r) ps += p1[r];
;   { auto rr = __builtin_amdgcn_permlane32_swap(__float_as_uint(ps), __float_as_uint(ps), false, false);
;     ps = __uint_as_float(rr[0]) + __uint_as_float(rr[1]); }
;   l_reg += ps;
;     ...
;   PK4(p0, 0, pa0); PK4(p0, 8, pa1); PK4(p1, 0, pa2); PK4(p1, 8, pa3);
; __device__ __forceinline__ void qkt(f32x16& p0, f32x16& p1, const bf16* Ks, const bf16x8* qr, int r32, int hi, const f32x16& negm) {
; #pragma unroll
;   for (int d0 = 0; d0 < 8; ++d0) { int cb = (d0 * 16 + hi * 8) * 2;
;     bf16x8 b0 = *reinterpret_cast<const bf16x8*>((const char*)Ks + KSWZ(r32, cb));
;     bf16x8 b1 = *reinterpret_cast<const bf16x8*>((const char*)Ks + KSWZ(32 + r32, cb));
;     if (d0 == 0) { p0 = __builtin_amdgcn_mfma_f32_32x32x16_bf16(b0, qr[0], negm, 0, 0, 0); p1 = __builtin_amdgcn_mfma_f32_32x32x16_bf16(b1, qr[0], negm, 0, 0, 0); }
;     else { p0 = __builtin_amdgcn_mfma_f32_32x32x16_bf16(b0, qr[d0], p0, 0, 0, 0); p1 = __builtin_amdgcn_mfma_f32_32x32x16_bf16(b1, qr[d0], p1, 0, 0, 0); } }
; }
	s_waitcnt lgkmcnt(3)
	v_mfma_f32_16x16x32_bf16 v[114:117], v[178:181], v[146:149], v[2:5]
	v_add_f32_e32 v250, v82, v250
	s_add_u32 s98, s98, 0x8000
	s_addc_u32 s99, s99, 0
	s_add_u32 s100, s100, 0x8000
	s_addc_u32 s101, s101, 0
	v_mfma_f32_16x16x32_bf16 v[118:121], v[178:181], v[162:165], v[2:5]
	ds_read_b128 v[178:181], v235 offset:49152
	v_add_f32_e32 v250, v83, v250
	v_add_f32_e32 v250, v84, v250
	s_waitcnt lgkmcnt(3)
	v_mfma_f32_16x16x32_bf16 v[122:125], v[182:185], v[146:149], v[2:5]
	v_add_f32_e32 v250, v85, v250
	s_add_u32 m0, s79, 32768
	s_nop 0
	global_load_lds_dwordx4 v246, s[98:99]
	v_mfma_f32_16x16x32_bf16 v[126:129], v[182:185], v[162:165], v[2:5]
	ds_read_b128 v[182:185], v235 offset:53248
	v_add_f32_e32 v250, v90, v250
	v_add_f32_e32 v250, v91, v250
	s_waitcnt lgkmcnt(3)
	v_mfma_f32_16x16x32_bf16 v[130:133], v[186:189], v[146:149], v[2:5]
	v_add_f32_e32 v250, v92, v250
	v_mfma_f32_16x16x32_bf16 v[134:137], v[186:189], v[162:165], v[2:5]
	ds_read_b128 v[186:189], v235 offset:57344
	v_add_f32_e32 v250, v93, v250
	v_cvt_pk_bf16_f32 v82, v82, v83
	s_waitcnt lgkmcnt(3)
	v_mfma_f32_16x16x32_bf16 v[138:141], v[190:193], v[146:149], v[2:5]
	v_cvt_pk_bf16_f32 v83, v84, v85
	s_add_u32 m0, s79, 33792
	s_nop 0
	global_load_lds_dwordx4 v247, s[98:99]
	v_mfma_f32_16x16x32_bf16 v[142:145], v[190:193], v[162:165], v[2:5]
	ds_read_b128 v[190:193], v235 offset:61440
	v_cvt_pk_bf16_f32 v84, v90, v91
	v_cvt_pk_bf16_f32 v85, v92, v93
	s_waitcnt lgkmcnt(3)
	v_mfma_f32_16x16x32_bf16 v[114:117], v[178:181], v[150:153], v[114:117]
	v_add_f32_e32 v251, v86, v251
	v_mfma_f32_16x16x32_bf16 v[118:121], v[178:181], v[166:169], v[118:121]
	ds_read_b128 v[178:181], v236 offset:49152
	v_add_f32_e32 v251, v87, v251
	v_add_f32_e32 v251, v88, v251
	s_waitcnt lgkmcnt(3)
	v_mfma_f32_16x16x32_bf16 v[122:125], v[182:185], v[150:153], v[122:125]
	v_add_f32_e32 v251, v89, v251
	s_add_u32 m0, s80, 16384
	s_nop 0
	global_load_lds_dwordx4 v248, s[100:101]
	v_mfma_f32_16x16x32_bf16 v[126:129], v[182:185], v[166:169], v[126:129]
	ds_read_b128 v[182:185], v236 offset:53248
	v_add_f32_e32 v251, v94, v251
	v_add_f32_e32 v251, v95, v251
	s_waitcnt lgkmcnt(3)
	v_mfma_f32_16x16x32_bf16 v[130:133], v[186:189], v[150:153], v[130:133]
	v_add_f32_e32 v251, v96, v251
	v_mfma_f32_16x16x32_bf16 v[134:137], v[186:189], v[166:169], v[134:137]
	ds_read_b128 v[186:189], v236 offset:57344
	v_add_f32_e32 v251, v97, v251
	v_cvt_pk_bf16_f32 v86, v86, v87
	s_waitcnt lgkmcnt(3)
	v_mfma_f32_16x16x32_bf16 v[138:141], v[190:193], v[150:153], v[138:141]
	v_cvt_pk_bf16_f32 v87, v88, v89
	s_add_u32 m0, s80, 17408
	s_nop 0
	global_load_lds_dwordx4 v249, s[100:101]
	v_mfma_f32_16x16x32_bf16 v[142:145], v[190:193], v[166:169], v[142:145]
	ds_read_b128 v[190:193], v236 offset:61440
	v_cvt_pk_bf16_f32 v88, v94, v95
	v_cvt_pk_bf16_f32 v89, v96, v97
	s_waitcnt lgkmcnt(3)
	v_mfma_f32_16x16x32_bf16 v[114:117], v[178:181], v[154:157], v[114:117]
	v_add_f32_e32 v250, v98, v250
	v_mfma_f32_16x16x32_bf16 v[118:121], v[178:181], v[170:173], v[118:121]
	ds_read_b128 v[178:181], v237 offset:49152
	v_add_f32_e32 v250, v99, v250
	v_add_f32_e32 v250, v100, v250
	s_waitcnt lgkmcnt(3)
	v_mfma_f32_16x16x32_bf16 v[122:125], v[182:185], v[154:157], v[122:125]
	v_add_f32_e32 v250, v101, v250
	v_mfma_f32_16x16x32_bf16 v[126:129], v[182:185], v[170:173], v[126:129]
	ds_read_b128 v[182:185], v237 offset:53248
	v_add_f32_e32 v250, v106, v250
	v_add_f32_e32 v250, v107, v250
	s_waitcnt lgkmcnt(3)
	v_mfma_f32_16x16x32_bf16 v[130:133], v[186:189], v[154:157], v[130:133]
	v_add_f32_e32 v250, v108, v250
	ds_read_b64_tr_b16 v[202:203], v238 offset:32768
	ds_read_b64_tr_b16 v[204:205], v238 offset:36864
	v_mfma_f32_16x16x32_bf16 v[134:137], v[186:189], v[170:173], v[134:137]
	ds_read_b128 v[186:189], v237 offset:57344
	v_add_f32_e32 v250, v109, v250
	v_cvt_pk_bf16_f32 v98, v98, v99
	s_waitcnt lgkmcnt(5)
	v_mfma_f32_16x16x32_bf16 v[138:141], v[190:193], v[154:157], v[138:141]
	v_cvt_pk_bf16_f32 v99, v100, v101
	ds_read_b64_tr_b16 v[206:207], v239 offset:32768
	ds_read_b64_tr_b16 v[208:209], v239 offset:36864
	v_mfma_f32_16x16x32_bf16 v[142:145], v[190:193], v[170:173], v[142:145]
	ds_read_b128 v[190:193], v237 offset:61440
	v_cvt_pk_bf16_f32 v100, v106, v107
	v_cvt_pk_bf16_f32 v101, v108, v109
	s_waitcnt lgkmcnt(7)
	v_mfma_f32_16x16x32_bf16 v[114:117], v[178:181], v[158:161], v[114:117]
	v_add_f32_e32 v251, v102, v251
	ds_read_b64_tr_b16 v[210:211], v240 offset:32768
	ds_read_b64_tr_b16 v[212:213], v240 offset:36864
	v_mfma_f32_16x16x32_bf16 v[118:121], v[178:181], v[174:177], v[118:121]
	v_add_f32_e32 v251, v103, v251
	v_add_f32_e32 v251, v104, v251
	s_waitcnt lgkmcnt(8)
	v_mfma_f32_16x16x32_bf16 v[122:125], v[182:185], v[158:161], v[122:125]
	v_add_f32_e32 v251, v105, v251
	ds_read_b64_tr_b16 v[214:215], v241 offset:32768
	ds_read_b64_tr_b16 v[216:217], v241 offset:36864
	v_mfma_f32_16x16x32_bf16 v[126:129], v[182:185], v[174:177], v[126:129]
	v_add_f32_e32 v251, v110, v251
	v_add_f32_e32 v251, v111, v251
	s_waitcnt lgkmcnt(7)
	v_mfma_f32_16x16x32_bf16 v[130:133], v[186:189], v[158:161], v[130:133]
	v_add_f32_e32 v251, v112, v251
	ds_read_b64_tr_b16 v[218:219], v242 offset:32768
	ds_read_b64_tr_b16 v[220:221], v242 offset:36864
	v_mfma_f32_16x16x32_bf16 v[134:137], v[186:189], v[174:177], v[134:137]
	v_add_f32_e32 v251, v113, v251
	v_cvt_pk_bf16_f32 v102, v102, v103
	s_waitcnt lgkmcnt(6)
; #define SBAR() __builtin_amdgcn_sched_barrier(0)
; __device__ __forceinline__ void partialSM(f32x16& p0, f32x16& p1, float mC) {
;   (void)mC; (void)p1;
;   for (int r = 0; r < 16; ++r) p0[r] = __builtin_amdgcn_exp2f(p0[r]);
; }
; __device__ __forceinline__ void finishSM(f32x16& p0, f32x16& p1, float& l_reg, bf16x8& pa0, bf16x8& pa1, bf16x8& pa2, bf16x8& pa3) {
;   for (int r = 0; r < 16; ++r) p1[r] = __builtin_amdgcn_exp2f(p1[r]);
; template <int D0> __device__ __forceinline__ void pv_one(f32x16& od, int vb, bf16x8 pa0, bf16x8 pa1, bf16x8 pa2, bf16x8 pa3) {
;   const s16x4 l0 = tr_read<v_rd_off(D0, 0, 0)>(vb), h0 = tr_read<v_rd_off(D0, 0, 1)>(vb), l1 = tr_read<v_rd_off(D0, 1, 0)>(vb), h1 = tr_read<v_rd_off(D0, 1, 1)>(vb);
;   const s16x4 l2 = tr_read<v_rd_off(D0, 2, 0)>(vb), h2 = tr_read<v_rd_off(D0, 2, 1)>(vb), l3 = tr_read<v_rd_off(D0, 3, 0)>(vb), h3 = tr_read<v_rd_off(D0, 3, 1)>(vb);
;   asm volatile("s_waitcnt lgkmcnt(0)" ::: "memory"); SBAR();
;     ...
;   od = __builtin_amdgcn_mfma_f32_32x32x16_bf16(pa0, PK(l0, h0), od, 0, 0, 0);
;   od = __builtin_amdgcn_mfma_f32_32x32x16_bf16(pa1, PK(l1, h1), od, 0, 0, 0);
;   od = __builtin_amdgcn_mfma_f32_32x32x16_bf16(pa2, PK(l2, h2), od, 0, 0, 0);
;   od = __builtin_amdgcn_mfma_f32_32x32x16_bf16(pa3, PK(l3, h3), od, 0, 0, 0);
;     ...
; }
; __device__ __forceinline__ void pv_d0(f32x16* o, int vb, bf16x8 pa0, bf16x8 pa1, bf16x8 pa2, bf16x8 pa3) {
;   pv_one<0>(o[0], vb, pa0, pa1, pa2, pa3); pv_one<1>(o[1], vb, pa0, pa1, pa2, pa3); pv_one<2>(o[2], vb, pa0, pa1, pa2, pa3); pv_one<3>(o[3], vb, pa0, pa1, pa2, pa3);
	v_mfma_f32_16x16x32_bf16 v[138:141], v[190:193], v[158:161], v[138:141]
	v_cvt_pk_bf16_f32 v103, v104, v105
	ds_read_b64_tr_b16 v[222:223], v243 offset:32768
	ds_read_b64_tr_b16 v[224:225], v243 offset:36864
	v_mfma_f32_16x16x32_bf16 v[142:145], v[190:193], v[174:177], v[142:145]
	v_cvt_pk_bf16_f32 v104, v110, v111
	v_cvt_pk_bf16_f32 v105, v112, v113
	v_mfma_f32_16x16x32_bf16 v[18:21], v[202:205], v[82:85], v[18:21]
	v_exp_f32_e32 v114, v114
	v_mfma_f32_16x16x32_bf16 v[22:25], v[202:205], v[86:89], v[22:25]
	ds_read_b64_tr_b16 v[202:203], v244 offset:32768
	ds_read_b64_tr_b16 v[204:205], v244 offset:36864
	v_exp_f32_e32 v115, v115
	v_mfma_f32_16x16x32_bf16 v[26:29], v[206:209], v[82:85], v[26:29]
	v_exp_f32_e32 v116, v116
	v_mfma_f32_16x16x32_bf16 v[30:33], v[206:209], v[86:89], v[30:33]
	ds_read_b64_tr_b16 v[206:207], v245 offset:32768
	ds_read_b64_tr_b16 v[208:209], v245 offset:36864
	v_exp_f32_e32 v117, v117
	s_waitcnt lgkmcnt(10)
	v_mfma_f32_16x16x32_bf16 v[34:37], v[210:213], v[82:85], v[34:37]
	v_exp_f32_e32 v118, v118
	v_mfma_f32_16x16x32_bf16 v[38:41], v[210:213], v[86:89], v[38:41]
	ds_read_b64_tr_b16 v[210:211], v238 offset:40960
	ds_read_b64_tr_b16 v[212:213], v238 offset:45056
	v_exp_f32_e32 v119, v119
	s_waitcnt lgkmcnt(10)
	v_mfma_f32_16x16x32_bf16 v[42:45], v[214:217], v[82:85], v[42:45]
	v_exp_f32_e32 v120, v120
	v_mfma_f32_16x16x32_bf16 v[46:49], v[214:217], v[86:89], v[46:49]
	ds_read_b64_tr_b16 v[214:215], v239 offset:40960
	ds_read_b64_tr_b16 v[216:217], v239 offset:45056
	v_exp_f32_e32 v121, v121
	s_waitcnt lgkmcnt(10)
	v_mfma_f32_16x16x32_bf16 v[50:53], v[218:221], v[82:85], v[50:53]
	v_exp_f32_e32 v122, v122
	v_mfma_f32_16x16x32_bf16 v[54:57], v[218:221], v[86:89], v[54:57]
	ds_read_b64_tr_b16 v[218:219], v240 offset:40960
	ds_read_b64_tr_b16 v[220:221], v240 offset:45056
	v_exp_f32_e32 v123, v123
	s_waitcnt lgkmcnt(10)
	v_mfma_f32_16x16x32_bf16 v[58:61], v[222:225], v[82:85], v[58:61]
	v_exp_f32_e32 v124, v124
	v_mfma_f32_16x16x32_bf16 v[62:65], v[222:225], v[86:89], v[62:65]
	ds_read_b64_tr_b16 v[222:223], v241 offset:40960
	ds_read_b64_tr_b16 v[224:225], v241 offset:45056
	v_exp_f32_e32 v125, v125
	s_waitcnt lgkmcnt(10)
	v_mfma_f32_16x16x32_bf16 v[66:69], v[202:205], v[82:85], v[66:69]
	v_exp_f32_e32 v126, v126
	v_mfma_f32_16x16x32_bf16 v[70:73], v[202:205], v[86:89], v[70:73]
	ds_read_b64_tr_b16 v[202:203], v242 offset:40960
	ds_read_b64_tr_b16 v[204:205], v242 offset:45056
	v_exp_f32_e32 v127, v127
	s_waitcnt lgkmcnt(10)
	v_mfma_f32_16x16x32_bf16 v[74:77], v[206:209], v[82:85], v[74:77]
	v_exp_f32_e32 v128, v128
	v_mfma_f32_16x16x32_bf16 v[78:81], v[206:209], v[86:89], v[78:81]
	ds_read_b64_tr_b16 v[206:207], v243 offset:40960
	ds_read_b64_tr_b16 v[208:209], v243 offset:45056
	v_exp_f32_e32 v129, v129
	s_waitcnt lgkmcnt(10)
	v_mfma_f32_16x16x32_bf16 v[18:21], v[210:213], v[98:101], v[18:21]
	v_exp_f32_e32 v130, v130
	v_mfma_f32_16x16x32_bf16 v[22:25], v[210:213], v[102:105], v[22:25]
	ds_read_b64_tr_b16 v[210:211], v244 offset:40960
	ds_read_b64_tr_b16 v[212:213], v244 offset:45056
	v_exp_f32_e32 v131, v131
	s_waitcnt lgkmcnt(10)
	v_mfma_f32_16x16x32_bf16 v[26:29], v[214:217], v[98:101], v[26:29]
	v_exp_f32_e32 v132, v132
	v_mfma_f32_16x16x32_bf16 v[30:33], v[214:217], v[102:105], v[30:33]
	ds_read_b64_tr_b16 v[214:215], v245 offset:40960
	ds_read_b64_tr_b16 v[216:217], v245 offset:45056
	v_exp_f32_e32 v133, v133
	s_waitcnt lgkmcnt(10)
	v_mfma_f32_16x16x32_bf16 v[34:37], v[218:221], v[98:101], v[34:37]
	v_exp_f32_e32 v134, v134
	v_mfma_f32_16x16x32_bf16 v[38:41], v[218:221], v[102:105], v[38:41]
	v_exp_f32_e32 v135, v135
	s_waitcnt lgkmcnt(8)
	v_mfma_f32_16x16x32_bf16 v[42:45], v[222:225], v[98:101], v[42:45]
	v_exp_f32_e32 v136, v136
	v_mfma_f32_16x16x32_bf16 v[46:49], v[222:225], v[102:105], v[46:49]
	v_exp_f32_e32 v137, v137
	s_waitcnt lgkmcnt(6)
	v_mfma_f32_16x16x32_bf16 v[50:53], v[202:205], v[98:101], v[50:53]
	v_exp_f32_e32 v138, v138
	ds_read_b128 v[178:181], v234 offset:0
	v_mfma_f32_16x16x32_bf16 v[54:57], v[202:205], v[102:105], v[54:57]
	v_exp_f32_e32 v139, v139
	s_waitcnt lgkmcnt(5)
	v_mfma_f32_16x16x32_bf16 v[58:61], v[206:209], v[98:101], v[58:61]
	v_exp_f32_e32 v140, v140
	ds_read_b128 v[182:185], v234 offset:4096
	v_mfma_f32_16x16x32_bf16 v[62:65], v[206:209], v[102:105], v[62:65]
	v_exp_f32_e32 v141, v141
	s_waitcnt lgkmcnt(4)
	v_mfma_f32_16x16x32_bf16 v[66:69], v[210:213], v[98:101], v[66:69]
	v_exp_f32_e32 v142, v142
	ds_read_b128 v[186:189], v234 offset:8192
	v_mfma_f32_16x16x32_bf16 v[70:73], v[210:213], v[102:105], v[70:73]
	v_exp_f32_e32 v143, v143
	s_waitcnt lgkmcnt(3)
	v_mfma_f32_16x16x32_bf16 v[74:77], v[214:217], v[98:101], v[74:77]
	v_exp_f32_e32 v144, v144
	ds_read_b128 v[190:193], v234 offset:12288
	v_mfma_f32_16x16x32_bf16 v[78:81], v[214:217], v[102:105], v[78:81]
	v_exp_f32_e32 v145, v145
	s_waitcnt vmcnt(4)
	s_barrier
; __device__ __forceinline__ void finishSM(f32x16& p0, f32x16& p1, float& l_reg, bf16x8& pa0, bf16x8& pa1, bf16x8& pa2, bf16x8& pa3) {
;   for (int r = 0; r < 16; ++r) p1[r] = __builtin_amdgcn_exp2f(p1[r]);
;   float ps = 0; for (int r = 0; r < 16; ++r) ps += p0[r]; for (int r = 0; r < 16; ++r) ps += p1[r];
;   { auto rr = __builtin_amdgcn_permlane32_swap(__float_as_uint(ps), __float_as_uint(ps), false, false);
;     ps = __uint_as_float(rr[0]) + __uint_as_float(rr[1]); }
;   l_reg += ps;
;     ...
;   PK4(p0, 0, pa0); PK4(p0, 8, pa1); PK4(p1, 0, pa2); PK4(p1, 8, pa3);
; __device__ __forceinline__ void qkt(f32x16& p0, f32x16& p1, const bf16* Ks, const bf16x8* qr, int r32, int hi, const f32x16& negm) {
; #pragma unroll
;   for (int d0 = 0; d0 < 8; ++d0) { int cb = (d0 * 16 + hi * 8) * 2;
;     bf16x8 b0 = *reinterpret_cast<const bf16x8*>((const char*)Ks + KSWZ(r32, cb));
;     bf16x8 b1 = *reinterpret_cast<const bf16x8*>((const char*)Ks + KSWZ(32 + r32, cb));
;     if (d0 == 0) { p0 = __builtin_amdgcn_mfma_f32_32x32x16_bf16(b0, qr[0], negm, 0, 0, 0); p1 = __builtin_amdgcn_mfma_f32_32x32x16_bf16(b1, qr[0], negm, 0, 0, 0); }
;     else { p0 = __builtin_amdgcn_mfma_f32_32x32x16_bf16(b0, qr[d0], p0, 0, 0, 0); p1 = __builtin_amdgcn_mfma_f32_32x32x16_bf16(b1, qr[d0], p1, 0, 0, 0); } }
; }
	s_waitcnt lgkmcnt(3)
	v_mfma_f32_16x16x32_bf16 v[82:85], v[178:181], v[146:149], v[2:5]
	v_add_f32_e32 v250, v114, v250
	s_add_u32 s98, s98, 0x8000
	s_addc_u32 s99, s99, 0
	s_add_u32 s100, s100, 0x8000
	s_addc_u32 s101, s101, 0
	v_mfma_f32_16x16x32_bf16 v[86:89], v[178:181], v[162:165], v[2:5]
	ds_read_b128 v[178:181], v235 offset:0
	v_add_f32_e32 v250, v115, v250
	v_add_f32_e32 v250, v116, v250
	s_waitcnt lgkmcnt(3)
	v_mfma_f32_16x16x32_bf16 v[90:93], v[182:185], v[146:149], v[2:5]
	v_add_f32_e32 v250, v117, v250
	s_add_u32 m0, s79, 49152
	s_nop 0
	global_load_lds_dwordx4 v246, s[98:99]
	v_mfma_f32_16x16x32_bf16 v[94:97], v[182:185], v[162:165], v[2:5]
	ds_read_b128 v[182:185], v235 offset:4096
	v_add_f32_e32 v250, v122, v250
	v_add_f32_e32 v250, v123, v250
	s_waitcnt lgkmcnt(3)
	v_mfma_f32_16x16x32_bf16 v[98:101], v[186:189], v[146:149], v[2:5]
	v_add_f32_e32 v250, v124, v250
	v_mfma_f32_16x16x32_bf16 v[102:105], v[186:189], v[162:165], v[2:5]
	ds_read_b128 v[186:189], v235 offset:8192
	v_add_f32_e32 v250, v125, v250
	v_cvt_pk_bf16_f32 v114, v114, v115
	s_waitcnt lgkmcnt(3)
	v_mfma_f32_16x16x32_bf16 v[106:109], v[190:193], v[146:149], v[2:5]
	v_cvt_pk_bf16_f32 v115, v116, v117
	s_add_u32 m0, s79, 50176
	s_nop 0
	global_load_lds_dwordx4 v247, s[98:99]
	v_mfma_f32_16x16x32_bf16 v[110:113], v[190:193], v[162:165], v[2:5]
	ds_read_b128 v[190:193], v235 offset:12288
	v_cvt_pk_bf16_f32 v116, v122, v123
	v_cvt_pk_bf16_f32 v117, v124, v125
	s_waitcnt lgkmcnt(3)
	v_mfma_f32_16x16x32_bf16 v[82:85], v[178:181], v[150:153], v[82:85]
	v_add_f32_e32 v251, v118, v251
	v_mfma_f32_16x16x32_bf16 v[86:89], v[178:181], v[166:169], v[86:89]
	ds_read_b128 v[178:181], v236 offset:0
	v_add_f32_e32 v251, v119, v251
	v_add_f32_e32 v251, v120, v251
	s_waitcnt lgkmcnt(3)
	v_mfma_f32_16x16x32_bf16 v[90:93], v[182:185], v[150:153], v[90:93]
	v_add_f32_e32 v251, v121, v251
	s_add_u32 m0, s80, 32768
	s_nop 0
	global_load_lds_dwordx4 v248, s[100:101]
	v_mfma_f32_16x16x32_bf16 v[94:97], v[182:185], v[166:169], v[94:97]
	ds_read_b128 v[182:185], v236 offset:4096
	v_add_f32_e32 v251, v126, v251
	v_add_f32_e32 v251, v127, v251
	s_waitcnt lgkmcnt(3)
	v_mfma_f32_16x16x32_bf16 v[98:101], v[186:189], v[150:153], v[98:101]
	v_add_f32_e32 v251, v128, v251
	v_mfma_f32_16x16x32_bf16 v[102:105], v[186:189], v[166:169], v[102:105]
	ds_read_b128 v[186:189], v236 offset:8192
	v_add_f32_e32 v251, v129, v251
	v_cvt_pk_bf16_f32 v118, v118, v119
	s_waitcnt lgkmcnt(3)
	v_mfma_f32_16x16x32_bf16 v[106:109], v[190:193], v[150:153], v[106:109]
	v_cvt_pk_bf16_f32 v119, v120, v121
	s_add_u32 m0, s80, 33792
	s_nop 0
	global_load_lds_dwordx4 v249, s[100:101]
	v_mfma_f32_16x16x32_bf16 v[110:113], v[190:193], v[166:169], v[110:113]
	ds_read_b128 v[190:193], v236 offset:12288
	v_cvt_pk_bf16_f32 v120, v126, v127
	v_cvt_pk_bf16_f32 v121, v128, v129
	s_waitcnt lgkmcnt(3)
	v_mfma_f32_16x16x32_bf16 v[82:85], v[178:181], v[154:157], v[82:85]
	v_add_f32_e32 v250, v130, v250
	v_mfma_f32_16x16x32_bf16 v[86:89], v[178:181], v[170:173], v[86:89]
	ds_read_b128 v[178:181], v237 offset:0
	v_add_f32_e32 v250, v131, v250
	v_add_f32_e32 v250, v132, v250
	s_waitcnt lgkmcnt(3)
	v_mfma_f32_16x16x32_bf16 v[90:93], v[182:185], v[154:157], v[90:93]
	v_add_f32_e32 v250, v133, v250
	v_mfma_f32_16x16x32_bf16 v[94:97], v[182:185], v[170:173], v[94:97]
	ds_read_b128 v[182:185], v237 offset:4096
	v_add_f32_e32 v250, v138, v250
	v_add_f32_e32 v250, v139, v250
	s_waitcnt lgkmcnt(3)
	v_mfma_f32_16x16x32_bf16 v[98:101], v[186:189], v[154:157], v[98:101]
	v_add_f32_e32 v250, v140, v250
	ds_read_b64_tr_b16 v[202:203], v238 offset:49152
	ds_read_b64_tr_b16 v[204:205], v238 offset:53248
	v_mfma_f32_16x16x32_bf16 v[102:105], v[186:189], v[170:173], v[102:105]
	ds_read_b128 v[186:189], v237 offset:8192
	v_add_f32_e32 v250, v141, v250
	v_cvt_pk_bf16_f32 v130, v130, v131
	s_waitcnt lgkmcnt(5)
	v_mfma_f32_16x16x32_bf16 v[106:109], v[190:193], v[154:157], v[106:109]
	v_cvt_pk_bf16_f32 v131, v132, v133
	ds_read_b64_tr_b16 v[206:207], v239 offset:49152
	ds_read_b64_tr_b16 v[208:209], v239 offset:53248
	v_mfma_f32_16x16x32_bf16 v[110:113], v[190:193], v[170:173], v[110:113]
	ds_read_b128 v[190:193], v237 offset:12288
	v_cvt_pk_bf16_f32 v132, v138, v139
	v_cvt_pk_bf16_f32 v133, v140, v141
	s_waitcnt lgkmcnt(7)
	v_mfma_f32_16x16x32_bf16 v[82:85], v[178:181], v[158:161], v[82:85]
	v_add_f32_e32 v251, v134, v251
	ds_read_b64_tr_b16 v[210:211], v240 offset:49152
	ds_read_b64_tr_b16 v[212:213], v240 offset:53248
	v_mfma_f32_16x16x32_bf16 v[86:89], v[178:181], v[174:177], v[86:89]
	v_add_f32_e32 v251, v135, v251
	v_add_f32_e32 v251, v136, v251
	s_waitcnt lgkmcnt(8)
	v_mfma_f32_16x16x32_bf16 v[90:93], v[182:185], v[158:161], v[90:93]
	v_add_f32_e32 v251, v137, v251
	ds_read_b64_tr_b16 v[214:215], v241 offset:49152
	ds_read_b64_tr_b16 v[216:217], v241 offset:53248
	v_mfma_f32_16x16x32_bf16 v[94:97], v[182:185], v[174:177], v[94:97]
	v_add_f32_e32 v251, v142, v251
	v_add_f32_e32 v251, v143, v251
	s_waitcnt lgkmcnt(7)
	v_mfma_f32_16x16x32_bf16 v[98:101], v[186:189], v[158:161], v[98:101]
	v_add_f32_e32 v251, v144, v251
	ds_read_b64_tr_b16 v[218:219], v242 offset:49152
	ds_read_b64_tr_b16 v[220:221], v242 offset:53248
	v_mfma_f32_16x16x32_bf16 v[102:105], v[186:189], v[174:177], v[102:105]
	v_add_f32_e32 v251, v145, v251
	v_cvt_pk_bf16_f32 v134, v134, v135
	s_waitcnt lgkmcnt(6)
; #define SBAR() __builtin_amdgcn_sched_barrier(0)
; #define SLOAD(i, k0) do { sr_[i].vs0 = St::ld8(&Vh[(long)((k0) + sr) * LDK + sc]); sr_[i].vs1 = St::ld8(&Vh[(long)((k0) + 32 + sr) * LDK + sc]); \
;     sr_[i].ks0 = St::ld8(&Kh[(long)((k0) + sr) * LDK + sc]); sr_[i].ks1 = St::ld8(&Kh[(long)((k0) + 32 + sr) * LDK + sc]); } while (0)
; #define SWAIT() do { if constexpr (SDEPTH == 2) asm volatile("s_waitcnt vmcnt(4)" ::: "memory"); else asm volatile("s_waitcnt vmcnt(0)" ::: "memory"); } while (0)
; template <int D0> __device__ __forceinline__ void pv_one(f32x16& od, int vb, bf16x8 pa0, bf16x8 pa1, bf16x8 pa2, bf16x8 pa3) {
;   const s16x4 l0 = tr_read<v_rd_off(D0, 0, 0)>(vb), h0 = tr_read<v_rd_off(D0, 0, 1)>(vb), l1 = tr_read<v_rd_off(D0, 1, 0)>(vb), h1 = tr_read<v_rd_off(D0, 1, 1)>(vb);
;   const s16x4 l2 = tr_read<v_rd_off(D0, 2, 0)>(vb), h2 = tr_read<v_rd_off(D0, 2, 1)>(vb), l3 = tr_read<v_rd_off(D0, 3, 0)>(vb), h3 = tr_read<v_rd_off(D0, 3, 1)>(vb);
;   asm volatile("s_waitcnt lgkmcnt(0)" ::: "memory"); SBAR();
;     ...
;   od = __builtin_amdgcn_mfma_f32_32x32x16_bf16(pa0, PK(l0, h0), od, 0, 0, 0);
;   od = __builtin_amdgcn_mfma_f32_32x32x16_bf16(pa1, PK(l1, h1), od, 0, 0, 0);
;   od = __builtin_amdgcn_mfma_f32_32x32x16_bf16(pa2, PK(l2, h2), od, 0, 0, 0);
;   od = __builtin_amdgcn_mfma_f32_32x32x16_bf16(pa3, PK(l3, h3), od, 0, 0, 0);
;     ...
; }
; __device__ __forceinline__ void pv_d0(f32x16* o, int vb, bf16x8 pa0, bf16x8 pa1, bf16x8 pa2, bf16x8 pa3) {
;   pv_one<0>(o[0], vb, pa0, pa1, pa2, pa3); pv_one<1>(o[1], vb, pa0, pa1, pa2, pa3); pv_one<2>(o[2], vb, pa0, pa1, pa2, pa3); pv_one<3>(o[3], vb, pa0, pa1, pa2, pa3);
; template <typename TQ> ...
;     ...
;   for (int j = 1; j + 1 < NT; j += 2) {
;     SBAR(); SLOAD(SO, (j + SDEPTH) * KVBLK); SBAR();
;     qkt(pB0, pB1, (bf16*)((char*)K_lds + SHM_K), qr, r32, hi, negm);
;     finishSM(pA0, pA1, l_reg, pa0, pa1, pa2, pa3); SBAR();
;     pv_d0(o, vb0, pa0, pa1, pa2, pa3); partialSM(pB0, pB1, mC);
;     __syncthreads(); SWAIT(); SWRITE(0, SE);
;     __syncthreads();
;     SBAR(); if (SDEPTH == 1 || j + 3 < NT) SLOAD(SE, (j + 1 + SDEPTH) * KVBLK); SBAR();
;     qkt(pA0, pA1, K_lds, qr, r32, hi, negm);
;     finishSM(pB0, pB1, l_reg, pa0, pa1, pa2, pa3); SBAR();
;     pv_d0(o, vb0 + (int)SHM_V, pa0, pa1, pa2, pa3); partialSM(pA0, pA1, mC);
;     __syncthreads(); SWAIT(); SWRITE(1, SO);
;     __syncthreads();
;   }
	v_mfma_f32_16x16x32_bf16 v[106:109], v[190:193], v[158:161], v[106:109]
	v_cvt_pk_bf16_f32 v135, v136, v137
	ds_read_b64_tr_b16 v[222:223], v243 offset:49152
	ds_read_b64_tr_b16 v[224:225], v243 offset:53248
	v_mfma_f32_16x16x32_bf16 v[110:113], v[190:193], v[174:177], v[110:113]
	v_cvt_pk_bf16_f32 v136, v142, v143
	v_cvt_pk_bf16_f32 v137, v144, v145
	v_mfma_f32_16x16x32_bf16 v[18:21], v[202:205], v[114:117], v[18:21]
	v_exp_f32_e32 v82, v82
	v_mfma_f32_16x16x32_bf16 v[22:25], v[202:205], v[118:121], v[22:25]
	ds_read_b64_tr_b16 v[202:203], v244 offset:49152
	ds_read_b64_tr_b16 v[204:205], v244 offset:53248
	v_exp_f32_e32 v83, v83
	v_mfma_f32_16x16x32_bf16 v[26:29], v[206:209], v[114:117], v[26:29]
	v_exp_f32_e32 v84, v84
	v_mfma_f32_16x16x32_bf16 v[30:33], v[206:209], v[118:121], v[30:33]
	ds_read_b64_tr_b16 v[206:207], v245 offset:49152
	ds_read_b64_tr_b16 v[208:209], v245 offset:53248
	v_exp_f32_e32 v85, v85
	s_waitcnt lgkmcnt(10)
	v_mfma_f32_16x16x32_bf16 v[34:37], v[210:213], v[114:117], v[34:37]
	v_exp_f32_e32 v86, v86
	v_mfma_f32_16x16x32_bf16 v[38:41], v[210:213], v[118:121], v[38:41]
	ds_read_b64_tr_b16 v[210:211], v238 offset:57344
	ds_read_b64_tr_b16 v[212:213], v238 offset:61440
	v_exp_f32_e32 v87, v87
	s_waitcnt lgkmcnt(10)
	v_mfma_f32_16x16x32_bf16 v[42:45], v[214:217], v[114:117], v[42:45]
	v_exp_f32_e32 v88, v88
	v_mfma_f32_16x16x32_bf16 v[46:49], v[214:217], v[118:121], v[46:49]
	ds_read_b64_tr_b16 v[214:215], v239 offset:57344
	ds_read_b64_tr_b16 v[216:217], v239 offset:61440
	v_exp_f32_e32 v89, v89
	s_waitcnt lgkmcnt(10)
	v_mfma_f32_16x16x32_bf16 v[50:53], v[218:221], v[114:117], v[50:53]
	v_exp_f32_e32 v90, v90
	v_mfma_f32_16x16x32_bf16 v[54:57], v[218:221], v[118:121], v[54:57]
	ds_read_b64_tr_b16 v[218:219], v240 offset:57344
	ds_read_b64_tr_b16 v[220:221], v240 offset:61440
	v_exp_f32_e32 v91, v91
	s_waitcnt lgkmcnt(10)
	v_mfma_f32_16x16x32_bf16 v[58:61], v[222:225], v[114:117], v[58:61]
	v_exp_f32_e32 v92, v92
	v_mfma_f32_16x16x32_bf16 v[62:65], v[222:225], v[118:121], v[62:65]
	ds_read_b64_tr_b16 v[222:223], v241 offset:57344
	ds_read_b64_tr_b16 v[224:225], v241 offset:61440
	v_exp_f32_e32 v93, v93
	s_waitcnt lgkmcnt(10)
	v_mfma_f32_16x16x32_bf16 v[66:69], v[202:205], v[114:117], v[66:69]
	v_exp_f32_e32 v94, v94
	v_mfma_f32_16x16x32_bf16 v[70:73], v[202:205], v[118:121], v[70:73]
	ds_read_b64_tr_b16 v[202:203], v242 offset:57344
	ds_read_b64_tr_b16 v[204:205], v242 offset:61440
	v_exp_f32_e32 v95, v95
	s_waitcnt lgkmcnt(10)
	v_mfma_f32_16x16x32_bf16 v[74:77], v[206:209], v[114:117], v[74:77]
	v_exp_f32_e32 v96, v96
	v_mfma_f32_16x16x32_bf16 v[78:81], v[206:209], v[118:121], v[78:81]
	ds_read_b64_tr_b16 v[206:207], v243 offset:57344
	ds_read_b64_tr_b16 v[208:209], v243 offset:61440
	v_exp_f32_e32 v97, v97
	s_waitcnt lgkmcnt(10)
	v_mfma_f32_16x16x32_bf16 v[18:21], v[210:213], v[130:133], v[18:21]
	v_exp_f32_e32 v98, v98
	v_mfma_f32_16x16x32_bf16 v[22:25], v[210:213], v[134:137], v[22:25]
	ds_read_b64_tr_b16 v[210:211], v244 offset:57344
	ds_read_b64_tr_b16 v[212:213], v244 offset:61440
	v_exp_f32_e32 v99, v99
	s_waitcnt lgkmcnt(10)
	v_mfma_f32_16x16x32_bf16 v[26:29], v[214:217], v[130:133], v[26:29]
	v_exp_f32_e32 v100, v100
	v_mfma_f32_16x16x32_bf16 v[30:33], v[214:217], v[134:137], v[30:33]
	ds_read_b64_tr_b16 v[214:215], v245 offset:57344
	ds_read_b64_tr_b16 v[216:217], v245 offset:61440
	v_exp_f32_e32 v101, v101
	s_waitcnt lgkmcnt(10)
	v_mfma_f32_16x16x32_bf16 v[34:37], v[218:221], v[130:133], v[34:37]
	v_exp_f32_e32 v102, v102
	v_mfma_f32_16x16x32_bf16 v[38:41], v[218:221], v[134:137], v[38:41]
	v_exp_f32_e32 v103, v103
	s_waitcnt lgkmcnt(8)
	v_mfma_f32_16x16x32_bf16 v[42:45], v[222:225], v[130:133], v[42:45]
	v_exp_f32_e32 v104, v104
	v_mfma_f32_16x16x32_bf16 v[46:49], v[222:225], v[134:137], v[46:49]
	v_exp_f32_e32 v105, v105
	s_waitcnt lgkmcnt(6)
	v_mfma_f32_16x16x32_bf16 v[50:53], v[202:205], v[130:133], v[50:53]
	v_exp_f32_e32 v106, v106
	ds_read_b128 v[178:181], v234 offset:16384
	v_mfma_f32_16x16x32_bf16 v[54:57], v[202:205], v[134:137], v[54:57]
	v_exp_f32_e32 v107, v107
	s_waitcnt lgkmcnt(5)
	v_mfma_f32_16x16x32_bf16 v[58:61], v[206:209], v[130:133], v[58:61]
	v_exp_f32_e32 v108, v108
	ds_read_b128 v[182:185], v234 offset:20480
	v_mfma_f32_16x16x32_bf16 v[62:65], v[206:209], v[134:137], v[62:65]
	v_exp_f32_e32 v109, v109
	s_waitcnt lgkmcnt(4)
	v_mfma_f32_16x16x32_bf16 v[66:69], v[210:213], v[130:133], v[66:69]
	v_exp_f32_e32 v110, v110
	ds_read_b128 v[186:189], v234 offset:24576
	v_mfma_f32_16x16x32_bf16 v[70:73], v[210:213], v[134:137], v[70:73]
	v_exp_f32_e32 v111, v111
	s_waitcnt lgkmcnt(3)
	v_mfma_f32_16x16x32_bf16 v[74:77], v[214:217], v[130:133], v[74:77]
	v_exp_f32_e32 v112, v112
	ds_read_b128 v[190:193], v234 offset:28672
	v_mfma_f32_16x16x32_bf16 v[78:81], v[214:217], v[134:137], v[78:81]
	v_exp_f32_e32 v113, v113
	s_waitcnt vmcnt(4)
	s_add_i32 s15, s15, 1
	s_cmp_lt_u32 s15, 32
	s_cbranch_scc1 .Lattn_loop
	s_barrier
; __device__ __forceinline__ void finishSM(f32x16& p0, f32x16& p1, float& l_reg, bf16x8& pa0, bf16x8& pa1, bf16x8& pa2, bf16x8& pa3) {
;   for (int r = 0; r < 16; ++r) p1[r] = __builtin_amdgcn_exp2f(p1[r]);
;   float ps = 0; for (int r = 0; r < 16; ++r) ps += p0[r]; for (int r = 0; r < 16; ++r) ps += p1[r];
;   { auto rr = __builtin_amdgcn_permlane32_swap(__float_as_uint(ps), __float_as_uint(ps), false, false);
;     ps = __uint_as_float(rr[0]) + __uint_as_float(rr[1]); }
;   l_reg += ps;
;     ...
;   PK4(p0, 0, pa0); PK4(p0, 8, pa1); PK4(p1, 0, pa2); PK4(p1, 8, pa3);
; __device__ __forceinline__ void qkt(f32x16& p0, f32x16& p1, const bf16* Ks, const bf16x8* qr, int r32, int hi, const f32x16& negm) {
; #pragma unroll
;   for (int d0 = 0; d0 < 8; ++d0) { int cb = (d0 * 16 + hi * 8) * 2;
;     bf16x8 b0 = *reinterpret_cast<const bf16x8*>((const char*)Ks + KSWZ(r32, cb));
;     bf16x8 b1 = *reinterpret_cast<const bf16x8*>((const char*)Ks + KSWZ(32 + r32, cb));
;     if (d0 == 0) { p0 = __builtin_amdgcn_mfma_f32_32x32x16_bf16(b0, qr[0], negm, 0, 0, 0); p1 = __builtin_amdgcn_mfma_f32_32x32x16_bf16(b1, qr[0], negm, 0, 0, 0); }
;     else { p0 = __builtin_amdgcn_mfma_f32_32x32x16_bf16(b0, qr[d0], p0, 0, 0, 0); p1 = __builtin_amdgcn_mfma_f32_32x32x16_bf16(b1, qr[d0], p1, 0, 0, 0); } }
; }
	s_waitcnt lgkmcnt(3)
	v_mfma_f32_16x16x32_bf16 v[114:117], v[178:181], v[146:149], v[2:5]
	v_add_f32_e32 v250, v82, v250
	s_add_u32 s98, s98, 0x8000
	s_addc_u32 s99, s99, 0
	s_add_u32 s100, s100, 0x8000
	s_addc_u32 s101, s101, 0
	v_mfma_f32_16x16x32_bf16 v[118:121], v[178:181], v[162:165], v[2:5]
	ds_read_b128 v[178:181], v235 offset:16384
	v_add_f32_e32 v250, v83, v250
	v_add_f32_e32 v250, v84, v250
	s_waitcnt lgkmcnt(3)
	v_mfma_f32_16x16x32_bf16 v[122:125], v[182:185], v[146:149], v[2:5]
	v_add_f32_e32 v250, v85, v250
	s_add_u32 m0, s80, 49152
	s_nop 0
	global_load_lds_dwordx4 v248, s[100:101]
	v_mfma_f32_16x16x32_bf16 v[126:129], v[182:185], v[162:165], v[2:5]
	ds_read_b128 v[182:185], v235 offset:20480
	v_add_f32_e32 v250, v90, v250
	v_add_f32_e32 v250, v91, v250
	s_waitcnt lgkmcnt(3)
	v_mfma_f32_16x16x32_bf16 v[130:133], v[186:189], v[146:149], v[2:5]
	v_add_f32_e32 v250, v92, v250
	v_mfma_f32_16x16x32_bf16 v[134:137], v[186:189], v[162:165], v[2:5]
	ds_read_b128 v[186:189], v235 offset:24576
	v_add_f32_e32 v250, v93, v250
	v_cvt_pk_bf16_f32 v82, v82, v83
	s_waitcnt lgkmcnt(3)
	v_mfma_f32_16x16x32_bf16 v[138:141], v[190:193], v[146:149], v[2:5]
	v_cvt_pk_bf16_f32 v83, v84, v85
	s_add_u32 m0, s80, 50176
	s_nop 0
	global_load_lds_dwordx4 v249, s[100:101]
	v_mfma_f32_16x16x32_bf16 v[142:145], v[190:193], v[162:165], v[2:5]
	ds_read_b128 v[190:193], v235 offset:28672
	v_cvt_pk_bf16_f32 v84, v90, v91
	v_cvt_pk_bf16_f32 v85, v92, v93
	s_waitcnt lgkmcnt(3)
	v_mfma_f32_16x16x32_bf16 v[114:117], v[178:181], v[150:153], v[114:117]
	v_add_f32_e32 v251, v86, v251
	v_mfma_f32_16x16x32_bf16 v[118:121], v[178:181], v[166:169], v[118:121]
	ds_read_b128 v[178:181], v236 offset:16384
	v_add_f32_e32 v251, v87, v251
	v_add_f32_e32 v251, v88, v251
	s_waitcnt lgkmcnt(3)
	v_mfma_f32_16x16x32_bf16 v[122:125], v[182:185], v[150:153], v[122:125]
	v_add_f32_e32 v251, v89, v251
	v_mfma_f32_16x16x32_bf16 v[126:129], v[182:185], v[166:169], v[126:129]
	ds_read_b128 v[182:185], v236 offset:20480
	v_add_f32_e32 v251, v94, v251
	v_add_f32_e32 v251, v95, v251
	s_waitcnt lgkmcnt(3)
	v_mfma_f32_16x16x32_bf16 v[130:133], v[186:189], v[150:153], v[130:133]
	v_add_f32_e32 v251, v96, v251
	v_mfma_f32_16x16x32_bf16 v[134:137], v[186:189], v[166:169], v[134:137]
	ds_read_b128 v[186:189], v236 offset:24576
	v_add_f32_e32 v251, v97, v251
	v_cvt_pk_bf16_f32 v86, v86, v87
	s_waitcnt lgkmcnt(3)
	v_mfma_f32_16x16x32_bf16 v[138:141], v[190:193], v[150:153], v[138:141]
	v_cvt_pk_bf16_f32 v87, v88, v89
	v_mfma_f32_16x16x32_bf16 v[142:145], v[190:193], v[166:169], v[142:145]
	ds_read_b128 v[190:193], v236 offset:28672
	v_cvt_pk_bf16_f32 v88, v94, v95
	v_cvt_pk_bf16_f32 v89, v96, v97
	s_waitcnt lgkmcnt(3)
	v_mfma_f32_16x16x32_bf16 v[114:117], v[178:181], v[154:157], v[114:117]
	v_add_f32_e32 v250, v98, v250
	v_mfma_f32_16x16x32_bf16 v[118:121], v[178:181], v[170:173], v[118:121]
	ds_read_b128 v[178:181], v237 offset:16384
	v_add_f32_e32 v250, v99, v250
	v_add_f32_e32 v250, v100, v250
	s_waitcnt lgkmcnt(3)
	v_mfma_f32_16x16x32_bf16 v[122:125], v[182:185], v[154:157], v[122:125]
	v_add_f32_e32 v250, v101, v250
	v_mfma_f32_16x16x32_bf16 v[126:129], v[182:185], v[170:173], v[126:129]
	ds_read_b128 v[182:185], v237 offset:20480
	v_add_f32_e32 v250, v106, v250
	v_add_f32_e32 v250, v107, v250
	s_waitcnt lgkmcnt(3)
	v_mfma_f32_16x16x32_bf16 v[130:133], v[186:189], v[154:157], v[130:133]
	v_add_f32_e32 v250, v108, v250
	ds_read_b64_tr_b16 v[202:203], v238 offset:0
	ds_read_b64_tr_b16 v[204:205], v238 offset:4096
	v_mfma_f32_16x16x32_bf16 v[134:137], v[186:189], v[170:173], v[134:137]
	ds_read_b128 v[186:189], v237 offset:24576
	v_add_f32_e32 v250, v109, v250
	v_cvt_pk_bf16_f32 v98, v98, v99
	s_waitcnt lgkmcnt(5)
	v_mfma_f32_16x16x32_bf16 v[138:141], v[190:193], v[154:157], v[138:141]
	v_cvt_pk_bf16_f32 v99, v100, v101
	ds_read_b64_tr_b16 v[206:207], v239 offset:0
	ds_read_b64_tr_b16 v[208:209], v239 offset:4096
	v_mfma_f32_16x16x32_bf16 v[142:145], v[190:193], v[170:173], v[142:145]
	ds_read_b128 v[190:193], v237 offset:28672
	v_cvt_pk_bf16_f32 v100, v106, v107
	v_cvt_pk_bf16_f32 v101, v108, v109
	s_waitcnt lgkmcnt(7)
	v_mfma_f32_16x16x32_bf16 v[114:117], v[178:181], v[158:161], v[114:117]
	v_add_f32_e32 v251, v102, v251
	ds_read_b64_tr_b16 v[210:211], v240 offset:0
	ds_read_b64_tr_b16 v[212:213], v240 offset:4096
	v_mfma_f32_16x16x32_bf16 v[118:121], v[178:181], v[174:177], v[118:121]
	v_add_f32_e32 v251, v103, v251
	v_add_f32_e32 v251, v104, v251
	s_waitcnt lgkmcnt(8)
	v_mfma_f32_16x16x32_bf16 v[122:125], v[182:185], v[158:161], v[122:125]
	v_add_f32_e32 v251, v105, v251
	ds_read_b64_tr_b16 v[214:215], v241 offset:0
	ds_read_b64_tr_b16 v[216:217], v241 offset:4096
	v_mfma_f32_16x16x32_bf16 v[126:129], v[182:185], v[174:177], v[126:129]
	v_add_f32_e32 v251, v110, v251
	v_add_f32_e32 v251, v111, v251
	s_waitcnt lgkmcnt(7)
	v_mfma_f32_16x16x32_bf16 v[130:133], v[186:189], v[158:161], v[130:133]
	v_add_f32_e32 v251, v112, v251
	ds_read_b64_tr_b16 v[218:219], v242 offset:0
	ds_read_b64_tr_b16 v[220:221], v242 offset:4096
	v_mfma_f32_16x16x32_bf16 v[134:137], v[186:189], v[174:177], v[134:137]
	v_add_f32_e32 v251, v113, v251
	v_cvt_pk_bf16_f32 v102, v102, v103
	s_waitcnt lgkmcnt(6)
; #define SBAR() __builtin_amdgcn_sched_barrier(0)
; __device__ __forceinline__ void partialSM(f32x16& p0, f32x16& p1, float mC) {
;   (void)mC; (void)p1;
;   for (int r = 0; r < 16; ++r) p0[r] = __builtin_amdgcn_exp2f(p0[r]);
; }
; __device__ __forceinline__ void finishSM(f32x16& p0, f32x16& p1, float& l_reg, bf16x8& pa0, bf16x8& pa1, bf16x8& pa2, bf16x8& pa3) {
;   for (int r = 0; r < 16; ++r) p1[r] = __builtin_amdgcn_exp2f(p1[r]);
; template <int D0> __device__ __forceinline__ void pv_one(f32x16& od, int vb, bf16x8 pa0, bf16x8 pa1, bf16x8 pa2, bf16x8 pa3) {
;   const s16x4 l0 = tr_read<v_rd_off(D0, 0, 0)>(vb), h0 = tr_read<v_rd_off(D0, 0, 1)>(vb), l1 = tr_read<v_rd_off(D0, 1, 0)>(vb), h1 = tr_read<v_rd_off(D0, 1, 1)>(vb);
;   const s16x4 l2 = tr_read<v_rd_off(D0, 2, 0)>(vb), h2 = tr_read<v_rd_off(D0, 2, 1)>(vb), l3 = tr_read<v_rd_off(D0, 3, 0)>(vb), h3 = tr_read<v_rd_off(D0, 3, 1)>(vb);
;   asm volatile("s_waitcnt lgkmcnt(0)" ::: "memory"); SBAR();
;     ...
;   od = __builtin_amdgcn_mfma_f32_32x32x16_bf16(pa0, PK(l0, h0), od, 0, 0, 0);
;   od = __builtin_amdgcn_mfma_f32_32x32x16_bf16(pa1, PK(l1, h1), od, 0, 0, 0);
;   od = __builtin_amdgcn_mfma_f32_32x32x16_bf16(pa2, PK(l2, h2), od, 0, 0, 0);
;   od = __builtin_amdgcn_mfma_f32_32x32x16_bf16(pa3, PK(l3, h3), od, 0, 0, 0);
;     ...
; }
; __device__ __forceinline__ void pv_d0(f32x16* o, int vb, bf16x8 pa0, bf16x8 pa1, bf16x8 pa2, bf16x8 pa3) {
;   pv_one<0>(o[0], vb, pa0, pa1, pa2, pa3); pv_one<1>(o[1], vb, pa0, pa1, pa2, pa3); pv_one<2>(o[2], vb, pa0, pa1, pa2, pa3); pv_one<3>(o[3], vb, pa0, pa1, pa2, pa3);
	v_mfma_f32_16x16x32_bf16 v[138:141], v[190:193], v[158:161], v[138:141]
	v_cvt_pk_bf16_f32 v103, v104, v105
	ds_read_b64_tr_b16 v[222:223], v243 offset:0
	ds_read_b64_tr_b16 v[224:225], v243 offset:4096
	v_mfma_f32_16x16x32_bf16 v[142:145], v[190:193], v[174:177], v[142:145]
	v_cvt_pk_bf16_f32 v104, v110, v111
	v_cvt_pk_bf16_f32 v105, v112, v113
	v_mfma_f32_16x16x32_bf16 v[18:21], v[202:205], v[82:85], v[18:21]
	v_exp_f32_e32 v114, v114
	v_mfma_f32_16x16x32_bf16 v[22:25], v[202:205], v[86:89], v[22:25]
	ds_read_b64_tr_b16 v[202:203], v244 offset:0
	ds_read_b64_tr_b16 v[204:205], v244 offset:4096
	v_exp_f32_e32 v115, v115
	v_mfma_f32_16x16x32_bf16 v[26:29], v[206:209], v[82:85], v[26:29]
	v_exp_f32_e32 v116, v116
	v_mfma_f32_16x16x32_bf16 v[30:33], v[206:209], v[86:89], v[30:33]
	ds_read_b64_tr_b16 v[206:207], v245 offset:0
	ds_read_b64_tr_b16 v[208:209], v245 offset:4096
	v_exp_f32_e32 v117, v117
	s_waitcnt lgkmcnt(10)
	v_mfma_f32_16x16x32_bf16 v[34:37], v[210:213], v[82:85], v[34:37]
	v_exp_f32_e32 v118, v118
	v_mfma_f32_16x16x32_bf16 v[38:41], v[210:213], v[86:89], v[38:41]
	ds_read_b64_tr_b16 v[210:211], v238 offset:8192
	ds_read_b64_tr_b16 v[212:213], v238 offset:12288
	v_exp_f32_e32 v119, v119
	s_waitcnt lgkmcnt(10)
	v_mfma_f32_16x16x32_bf16 v[42:45], v[214:217], v[82:85], v[42:45]
	v_exp_f32_e32 v120, v120
	v_mfma_f32_16x16x32_bf16 v[46:49], v[214:217], v[86:89], v[46:49]
	ds_read_b64_tr_b16 v[214:215], v239 offset:8192
	ds_read_b64_tr_b16 v[216:217], v239 offset:12288
	v_exp_f32_e32 v121, v121
	s_waitcnt lgkmcnt(10)
	v_mfma_f32_16x16x32_bf16 v[50:53], v[218:221], v[82:85], v[50:53]
	v_exp_f32_e32 v122, v122
	v_mfma_f32_16x16x32_bf16 v[54:57], v[218:221], v[86:89], v[54:57]
	ds_read_b64_tr_b16 v[218:219], v240 offset:8192
	ds_read_b64_tr_b16 v[220:221], v240 offset:12288
	v_exp_f32_e32 v123, v123
	s_waitcnt lgkmcnt(10)
	v_mfma_f32_16x16x32_bf16 v[58:61], v[222:225], v[82:85], v[58:61]
	v_exp_f32_e32 v124, v124
	v_mfma_f32_16x16x32_bf16 v[62:65], v[222:225], v[86:89], v[62:65]
	ds_read_b64_tr_b16 v[222:223], v241 offset:8192
	ds_read_b64_tr_b16 v[224:225], v241 offset:12288
	v_exp_f32_e32 v125, v125
	s_waitcnt lgkmcnt(10)
	v_mfma_f32_16x16x32_bf16 v[66:69], v[202:205], v[82:85], v[66:69]
	v_exp_f32_e32 v126, v126
	v_mfma_f32_16x16x32_bf16 v[70:73], v[202:205], v[86:89], v[70:73]
	ds_read_b64_tr_b16 v[202:203], v242 offset:8192
	ds_read_b64_tr_b16 v[204:205], v242 offset:12288
	v_exp_f32_e32 v127, v127
	s_waitcnt lgkmcnt(10)
	v_mfma_f32_16x16x32_bf16 v[74:77], v[206:209], v[82:85], v[74:77]
	v_exp_f32_e32 v128, v128
	v_mfma_f32_16x16x32_bf16 v[78:81], v[206:209], v[86:89], v[78:81]
	ds_read_b64_tr_b16 v[206:207], v243 offset:8192
	ds_read_b64_tr_b16 v[208:209], v243 offset:12288
	v_exp_f32_e32 v129, v129
	s_waitcnt lgkmcnt(10)
	v_mfma_f32_16x16x32_bf16 v[18:21], v[210:213], v[98:101], v[18:21]
	v_exp_f32_e32 v130, v130
	v_mfma_f32_16x16x32_bf16 v[22:25], v[210:213], v[102:105], v[22:25]
	ds_read_b64_tr_b16 v[210:211], v244 offset:8192
	ds_read_b64_tr_b16 v[212:213], v244 offset:12288
	v_exp_f32_e32 v131, v131
	s_waitcnt lgkmcnt(10)
	v_mfma_f32_16x16x32_bf16 v[26:29], v[214:217], v[98:101], v[26:29]
	v_exp_f32_e32 v132, v132
	v_mfma_f32_16x16x32_bf16 v[30:33], v[214:217], v[102:105], v[30:33]
	ds_read_b64_tr_b16 v[214:215], v245 offset:8192
	ds_read_b64_tr_b16 v[216:217], v245 offset:12288
	v_exp_f32_e32 v133, v133
	s_waitcnt lgkmcnt(10)
	v_mfma_f32_16x16x32_bf16 v[34:37], v[218:221], v[98:101], v[34:37]
	v_exp_f32_e32 v134, v134
	v_mfma_f32_16x16x32_bf16 v[38:41], v[218:221], v[102:105], v[38:41]
	v_exp_f32_e32 v135, v135
	s_waitcnt lgkmcnt(8)
	v_mfma_f32_16x16x32_bf16 v[42:45], v[222:225], v[98:101], v[42:45]
	v_exp_f32_e32 v136, v136
	v_mfma_f32_16x16x32_bf16 v[46:49], v[222:225], v[102:105], v[46:49]
	v_exp_f32_e32 v137, v137
	s_waitcnt lgkmcnt(6)
	v_mfma_f32_16x16x32_bf16 v[50:53], v[202:205], v[98:101], v[50:53]
	v_exp_f32_e32 v138, v138
	ds_read_b128 v[178:181], v234 offset:32768
	v_mfma_f32_16x16x32_bf16 v[54:57], v[202:205], v[102:105], v[54:57]
	v_exp_f32_e32 v139, v139
	s_waitcnt lgkmcnt(5)
	v_mfma_f32_16x16x32_bf16 v[58:61], v[206:209], v[98:101], v[58:61]
	v_exp_f32_e32 v140, v140
	ds_read_b128 v[182:185], v234 offset:36864
	v_mfma_f32_16x16x32_bf16 v[62:65], v[206:209], v[102:105], v[62:65]
	v_exp_f32_e32 v141, v141
	s_waitcnt lgkmcnt(4)
	v_mfma_f32_16x16x32_bf16 v[66:69], v[210:213], v[98:101], v[66:69]
	v_exp_f32_e32 v142, v142
	ds_read_b128 v[186:189], v234 offset:40960
	v_mfma_f32_16x16x32_bf16 v[70:73], v[210:213], v[102:105], v[70:73]
	v_exp_f32_e32 v143, v143
	s_waitcnt lgkmcnt(3)
	v_mfma_f32_16x16x32_bf16 v[74:77], v[214:217], v[98:101], v[74:77]
	v_exp_f32_e32 v144, v144
	ds_read_b128 v[190:193], v234 offset:45056
	v_mfma_f32_16x16x32_bf16 v[78:81], v[214:217], v[102:105], v[78:81]
	v_exp_f32_e32 v145, v145
	s_waitcnt vmcnt(2)
	s_barrier
; __device__ __forceinline__ void finishSM(f32x16& p0, f32x16& p1, float& l_reg, bf16x8& pa0, bf16x8& pa1, bf16x8& pa2, bf16x8& pa3) {
;   for (int r = 0; r < 16; ++r) p1[r] = __builtin_amdgcn_exp2f(p1[r]);
;   float ps = 0; for (int r = 0; r < 16; ++r) ps += p0[r]; for (int r = 0; r < 16; ++r) ps += p1[r];
;   { auto rr = __builtin_amdgcn_permlane32_swap(__float_as_uint(ps), __float_as_uint(ps), false, false);
;     ps = __uint_as_float(rr[0]) + __uint_as_float(rr[1]); }
;   l_reg += ps;
;     ...
;   PK4(p0, 0, pa0); PK4(p0, 8, pa1); PK4(p1, 0, pa2); PK4(p1, 8, pa3);
; __device__ __forceinline__ void qkt(f32x16& p0, f32x16& p1, const bf16* Ks, const bf16x8* qr, int r32, int hi, const f32x16& negm) {
; #pragma unroll
;   for (int d0 = 0; d0 < 8; ++d0) { int cb = (d0 * 16 + hi * 8) * 2;
;     bf16x8 b0 = *reinterpret_cast<const bf16x8*>((const char*)Ks + KSWZ(r32, cb));
;     bf16x8 b1 = *reinterpret_cast<const bf16x8*>((const char*)Ks + KSWZ(32 + r32, cb));
;     if (d0 == 0) { p0 = __builtin_amdgcn_mfma_f32_32x32x16_bf16(b0, qr[0], negm, 0, 0, 0); p1 = __builtin_amdgcn_mfma_f32_32x32x16_bf16(b1, qr[0], negm, 0, 0, 0); }
;     else { p0 = __builtin_amdgcn_mfma_f32_32x32x16_bf16(b0, qr[d0], p0, 0, 0, 0); p1 = __builtin_amdgcn_mfma_f32_32x32x16_bf16(b1, qr[d0], p1, 0, 0, 0); } }
; }
	s_waitcnt lgkmcnt(3)
	v_mfma_f32_16x16x32_bf16 v[82:85], v[178:181], v[146:149], v[2:5]
	v_add_f32_e32 v250, v114, v250
	v_mfma_f32_16x16x32_bf16 v[86:89], v[178:181], v[162:165], v[2:5]
	ds_read_b128 v[178:181], v235 offset:32768
	v_add_f32_e32 v250, v115, v250
	v_add_f32_e32 v250, v116, v250
	s_waitcnt lgkmcnt(3)
	v_mfma_f32_16x16x32_bf16 v[90:93], v[182:185], v[146:149], v[2:5]
	v_add_f32_e32 v250, v117, v250
	v_mfma_f32_16x16x32_bf16 v[94:97], v[182:185], v[162:165], v[2:5]
	ds_read_b128 v[182:185], v235 offset:36864
	v_add_f32_e32 v250, v122, v250
	v_add_f32_e32 v250, v123, v250
	s_waitcnt lgkmcnt(3)
	v_mfma_f32_16x16x32_bf16 v[98:101], v[186:189], v[146:149], v[2:5]
	v_add_f32_e32 v250, v124, v250
	v_mfma_f32_16x16x32_bf16 v[102:105], v[186:189], v[162:165], v[2:5]
	ds_read_b128 v[186:189], v235 offset:40960
	v_add_f32_e32 v250, v125, v250
	v_cvt_pk_bf16_f32 v114, v114, v115
	s_waitcnt lgkmcnt(3)
	v_mfma_f32_16x16x32_bf16 v[106:109], v[190:193], v[146:149], v[2:5]
	v_cvt_pk_bf16_f32 v115, v116, v117
	v_mfma_f32_16x16x32_bf16 v[110:113], v[190:193], v[162:165], v[2:5]
	ds_read_b128 v[190:193], v235 offset:45056
	v_cvt_pk_bf16_f32 v116, v122, v123
	v_cvt_pk_bf16_f32 v117, v124, v125
	s_waitcnt lgkmcnt(3)
	v_mfma_f32_16x16x32_bf16 v[82:85], v[178:181], v[150:153], v[82:85]
	v_add_f32_e32 v251, v118, v251
	v_mfma_f32_16x16x32_bf16 v[86:89], v[178:181], v[166:169], v[86:89]
	ds_read_b128 v[178:181], v236 offset:32768
	v_add_f32_e32 v251, v119, v251
	v_add_f32_e32 v251, v120, v251
	s_waitcnt lgkmcnt(3)
	v_mfma_f32_16x16x32_bf16 v[90:93], v[182:185], v[150:153], v[90:93]
	v_add_f32_e32 v251, v121, v251
	v_mfma_f32_16x16x32_bf16 v[94:97], v[182:185], v[166:169], v[94:97]
	ds_read_b128 v[182:185], v236 offset:36864
	v_add_f32_e32 v251, v126, v251
	v_add_f32_e32 v251, v127, v251
	s_waitcnt lgkmcnt(3)
	v_mfma_f32_16x16x32_bf16 v[98:101], v[186:189], v[150:153], v[98:101]
	v_add_f32_e32 v251, v128, v251
	v_mfma_f32_16x16x32_bf16 v[102:105], v[186:189], v[166:169], v[102:105]
	ds_read_b128 v[186:189], v236 offset:40960
	v_add_f32_e32 v251, v129, v251
	v_cvt_pk_bf16_f32 v118, v118, v119
	s_waitcnt lgkmcnt(3)
	v_mfma_f32_16x16x32_bf16 v[106:109], v[190:193], v[150:153], v[106:109]
	v_cvt_pk_bf16_f32 v119, v120, v121
	v_mfma_f32_16x16x32_bf16 v[110:113], v[190:193], v[166:169], v[110:113]
	ds_read_b128 v[190:193], v236 offset:45056
	v_cvt_pk_bf16_f32 v120, v126, v127
	v_cvt_pk_bf16_f32 v121, v128, v129
	s_waitcnt lgkmcnt(3)
	v_mfma_f32_16x16x32_bf16 v[82:85], v[178:181], v[154:157], v[82:85]
	v_add_f32_e32 v250, v130, v250
	v_mfma_f32_16x16x32_bf16 v[86:89], v[178:181], v[170:173], v[86:89]
	ds_read_b128 v[178:181], v237 offset:32768
	v_add_f32_e32 v250, v131, v250
	v_add_f32_e32 v250, v132, v250
	s_waitcnt lgkmcnt(3)
	v_mfma_f32_16x16x32_bf16 v[90:93], v[182:185], v[154:157], v[90:93]
	v_add_f32_e32 v250, v133, v250
	v_mfma_f32_16x16x32_bf16 v[94:97], v[182:185], v[170:173], v[94:97]
	ds_read_b128 v[182:185], v237 offset:36864
	v_add_f32_e32 v250, v138, v250
	v_add_f32_e32 v250, v139, v250
	s_waitcnt lgkmcnt(3)
	v_mfma_f32_16x16x32_bf16 v[98:101], v[186:189], v[154:157], v[98:101]
	v_add_f32_e32 v250, v140, v250
	ds_read_b64_tr_b16 v[202:203], v238 offset:16384
	ds_read_b64_tr_b16 v[204:205], v238 offset:20480
	v_mfma_f32_16x16x32_bf16 v[102:105], v[186:189], v[170:173], v[102:105]
	ds_read_b128 v[186:189], v237 offset:40960
	v_add_f32_e32 v250, v141, v250
	v_cvt_pk_bf16_f32 v130, v130, v131
	s_waitcnt lgkmcnt(5)
	v_mfma_f32_16x16x32_bf16 v[106:109], v[190:193], v[154:157], v[106:109]
	v_cvt_pk_bf16_f32 v131, v132, v133
	ds_read_b64_tr_b16 v[206:207], v239 offset:16384
	ds_read_b64_tr_b16 v[208:209], v239 offset:20480
	v_mfma_f32_16x16x32_bf16 v[110:113], v[190:193], v[170:173], v[110:113]
	ds_read_b128 v[190:193], v237 offset:45056
	v_cvt_pk_bf16_f32 v132, v138, v139
	v_cvt_pk_bf16_f32 v133, v140, v141
	s_waitcnt lgkmcnt(7)
	v_mfma_f32_16x16x32_bf16 v[82:85], v[178:181], v[158:161], v[82:85]
	v_add_f32_e32 v251, v134, v251
	ds_read_b64_tr_b16 v[210:211], v240 offset:16384
	ds_read_b64_tr_b16 v[212:213], v240 offset:20480
	v_mfma_f32_16x16x32_bf16 v[86:89], v[178:181], v[174:177], v[86:89]
	v_add_f32_e32 v251, v135, v251
	v_add_f32_e32 v251, v136, v251
	s_waitcnt lgkmcnt(8)
	v_mfma_f32_16x16x32_bf16 v[90:93], v[182:185], v[158:161], v[90:93]
	v_add_f32_e32 v251, v137, v251
	ds_read_b64_tr_b16 v[214:215], v241 offset:16384
	ds_read_b64_tr_b16 v[216:217], v241 offset:20480
	v_mfma_f32_16x16x32_bf16 v[94:97], v[182:185], v[174:177], v[94:97]
	v_add_f32_e32 v251, v142, v251
	v_add_f32_e32 v251, v143, v251
	s_waitcnt lgkmcnt(7)
	v_mfma_f32_16x16x32_bf16 v[98:101], v[186:189], v[158:161], v[98:101]
	v_add_f32_e32 v251, v144, v251
	ds_read_b64_tr_b16 v[218:219], v242 offset:16384
	ds_read_b64_tr_b16 v[220:221], v242 offset:20480
	v_mfma_f32_16x16x32_bf16 v[102:105], v[186:189], v[174:177], v[102:105]
	v_add_f32_e32 v251, v145, v251
	v_cvt_pk_bf16_f32 v134, v134, v135
	s_waitcnt lgkmcnt(6)
	v_mfma_f32_16x16x32_bf16 v[106:109], v[190:193], v[158:161], v[106:109]
	v_cvt_pk_bf16_f32 v135, v136, v137
	ds_read_b64_tr_b16 v[222:223], v243 offset:16384
	ds_read_b64_tr_b16 v[224:225], v243 offset:20480
	v_mfma_f32_16x16x32_bf16 v[110:113], v[190:193], v[174:177], v[110:113]
	v_cvt_pk_bf16_f32 v136, v142, v143
	v_cvt_pk_bf16_f32 v137, v144, v145
	v_mfma_f32_16x16x32_bf16 v[18:21], v[202:205], v[114:117], v[18:21]
	v_exp_f32_e32 v82, v82
	v_mfma_f32_16x16x32_bf16 v[22:25], v[202:205], v[118:121], v[22:25]
	ds_read_b64_tr_b16 v[202:203], v244 offset:16384
	ds_read_b64_tr_b16 v[204:205], v244 offset:20480
	v_exp_f32_e32 v83, v83
	v_mfma_f32_16x16x32_bf16 v[26:29], v[206:209], v[114:117], v[26:29]
	v_exp_f32_e32 v84, v84
	v_mfma_f32_16x16x32_bf16 v[30:33], v[206:209], v[118:121], v[30:33]
	ds_read_b64_tr_b16 v[206:207], v245 offset:16384
	ds_read_b64_tr_b16 v[208:209], v245 offset:20480
	v_exp_f32_e32 v85, v85
	s_waitcnt lgkmcnt(10)
; #define SBAR() __builtin_amdgcn_sched_barrier(0)
; __device__ __forceinline__ void qkt(f32x16& p0, f32x16& p1, const bf16* Ks, const bf16x8* qr, int r32, int hi, const f32x16& negm) {
; #pragma unroll
;   for (int d0 = 0; d0 < 8; ++d0) { int cb = (d0 * 16 + hi * 8) * 2;
;     bf16x8 b0 = *reinterpret_cast<const bf16x8*>((const char*)Ks + KSWZ(r32, cb));
;     bf16x8 b1 = *reinterpret_cast<const bf16x8*>((const char*)Ks + KSWZ(32 + r32, cb));
;     if (d0 == 0) { p0 = __builtin_amdgcn_mfma_f32_32x32x16_bf16(b0, qr[0], negm, 0, 0, 0); p1 = __builtin_amdgcn_mfma_f32_32x32x16_bf16(b1, qr[0], negm, 0, 0, 0); }
;     else { p0 = __builtin_amdgcn_mfma_f32_32x32x16_bf16(b0, qr[d0], p0, 0, 0, 0); p1 = __builtin_amdgcn_mfma_f32_32x32x16_bf16(b1, qr[d0], p1, 0, 0, 0); } }
; }
; template <int D0> __device__ __forceinline__ void pv_one(f32x16& od, int vb, bf16x8 pa0, bf16x8 pa1, bf16x8 pa2, bf16x8 pa3) {
;   const s16x4 l0 = tr_read<v_rd_off(D0, 0, 0)>(vb), h0 = tr_read<v_rd_off(D0, 0, 1)>(vb), l1 = tr_read<v_rd_off(D0, 1, 0)>(vb), h1 = tr_read<v_rd_off(D0, 1, 1)>(vb);
;   const s16x4 l2 = tr_read<v_rd_off(D0, 2, 0)>(vb), h2 = tr_read<v_rd_off(D0, 2, 1)>(vb), l3 = tr_read<v_rd_off(D0, 3, 0)>(vb), h3 = tr_read<v_rd_off(D0, 3, 1)>(vb);
;   asm volatile("s_waitcnt lgkmcnt(0)" ::: "memory"); SBAR();
;     ...
;   od = __builtin_amdgcn_mfma_f32_32x32x16_bf16(pa0, PK(l0, h0), od, 0, 0, 0);
;   od = __builtin_amdgcn_mfma_f32_32x32x16_bf16(pa1, PK(l1, h1), od, 0, 0, 0);
;   od = __builtin_amdgcn_mfma_f32_32x32x16_bf16(pa2, PK(l2, h2), od, 0, 0, 0);
;   od = __builtin_amdgcn_mfma_f32_32x32x16_bf16(pa3, PK(l3, h3), od, 0, 0, 0);
;     ...
; }
; __device__ __forceinline__ void pv_d0(f32x16* o, int vb, bf16x8 pa0, bf16x8 pa1, bf16x8 pa2, bf16x8 pa3) {
;   pv_one<0>(o[0], vb, pa0, pa1, pa2, pa3); pv_one<1>(o[1], vb, pa0, pa1, pa2, pa3); pv_one<2>(o[2], vb, pa0, pa1, pa2, pa3); pv_one<3>(o[3], vb, pa0, pa1, pa2, pa3);
	v_mfma_f32_16x16x32_bf16 v[34:37], v[210:213], v[114:117], v[34:37]
	v_exp_f32_e32 v86, v86
	v_mfma_f32_16x16x32_bf16 v[38:41], v[210:213], v[118:121], v[38:41]
	ds_read_b64_tr_b16 v[210:211], v238 offset:24576
	ds_read_b64_tr_b16 v[212:213], v238 offset:28672
	v_exp_f32_e32 v87, v87
	s_waitcnt lgkmcnt(10)
	v_mfma_f32_16x16x32_bf16 v[42:45], v[214:217], v[114:117], v[42:45]
	v_exp_f32_e32 v88, v88
	v_mfma_f32_16x16x32_bf16 v[46:49], v[214:217], v[118:121], v[46:49]
	ds_read_b64_tr_b16 v[214:215], v239 offset:24576
	ds_read_b64_tr_b16 v[216:217], v239 offset:28672
	v_exp_f32_e32 v89, v89
	s_waitcnt lgkmcnt(10)
	v_mfma_f32_16x16x32_bf16 v[50:53], v[218:221], v[114:117], v[50:53]
	v_exp_f32_e32 v90, v90
	v_mfma_f32_16x16x32_bf16 v[54:57], v[218:221], v[118:121], v[54:57]
	ds_read_b64_tr_b16 v[218:219], v240 offset:24576
	ds_read_b64_tr_b16 v[220:221], v240 offset:28672
	v_exp_f32_e32 v91, v91
	s_waitcnt lgkmcnt(10)
	v_mfma_f32_16x16x32_bf16 v[58:61], v[222:225], v[114:117], v[58:61]
	v_exp_f32_e32 v92, v92
	v_mfma_f32_16x16x32_bf16 v[62:65], v[222:225], v[118:121], v[62:65]
	ds_read_b64_tr_b16 v[222:223], v241 offset:24576
	ds_read_b64_tr_b16 v[224:225], v241 offset:28672
	v_exp_f32_e32 v93, v93
	s_waitcnt lgkmcnt(10)
	v_mfma_f32_16x16x32_bf16 v[66:69], v[202:205], v[114:117], v[66:69]
	v_exp_f32_e32 v94, v94
	v_mfma_f32_16x16x32_bf16 v[70:73], v[202:205], v[118:121], v[70:73]
	ds_read_b64_tr_b16 v[202:203], v242 offset:24576
	ds_read_b64_tr_b16 v[204:205], v242 offset:28672
	v_exp_f32_e32 v95, v95
	s_waitcnt lgkmcnt(10)
	v_mfma_f32_16x16x32_bf16 v[74:77], v[206:209], v[114:117], v[74:77]
	v_exp_f32_e32 v96, v96
	v_mfma_f32_16x16x32_bf16 v[78:81], v[206:209], v[118:121], v[78:81]
	ds_read_b64_tr_b16 v[206:207], v243 offset:24576
	ds_read_b64_tr_b16 v[208:209], v243 offset:28672
	v_exp_f32_e32 v97, v97
	s_waitcnt lgkmcnt(10)
	v_mfma_f32_16x16x32_bf16 v[18:21], v[210:213], v[130:133], v[18:21]
	v_exp_f32_e32 v98, v98
	v_mfma_f32_16x16x32_bf16 v[22:25], v[210:213], v[134:137], v[22:25]
	ds_read_b64_tr_b16 v[210:211], v244 offset:24576
	ds_read_b64_tr_b16 v[212:213], v244 offset:28672
	v_exp_f32_e32 v99, v99
	s_waitcnt lgkmcnt(10)
	v_mfma_f32_16x16x32_bf16 v[26:29], v[214:217], v[130:133], v[26:29]
	v_exp_f32_e32 v100, v100
	v_mfma_f32_16x16x32_bf16 v[30:33], v[214:217], v[134:137], v[30:33]
	ds_read_b64_tr_b16 v[214:215], v245 offset:24576
	ds_read_b64_tr_b16 v[216:217], v245 offset:28672
	v_exp_f32_e32 v101, v101
	s_waitcnt lgkmcnt(10)
	v_mfma_f32_16x16x32_bf16 v[34:37], v[218:221], v[130:133], v[34:37]
	v_exp_f32_e32 v102, v102
	v_mfma_f32_16x16x32_bf16 v[38:41], v[218:221], v[134:137], v[38:41]
	v_exp_f32_e32 v103, v103
	s_waitcnt lgkmcnt(8)
	v_mfma_f32_16x16x32_bf16 v[42:45], v[222:225], v[130:133], v[42:45]
	v_exp_f32_e32 v104, v104
	v_mfma_f32_16x16x32_bf16 v[46:49], v[222:225], v[134:137], v[46:49]
	v_exp_f32_e32 v105, v105
	s_waitcnt lgkmcnt(6)
	v_mfma_f32_16x16x32_bf16 v[50:53], v[202:205], v[130:133], v[50:53]
	v_exp_f32_e32 v106, v106
	ds_read_b128 v[178:181], v234 offset:49152
	v_mfma_f32_16x16x32_bf16 v[54:57], v[202:205], v[134:137], v[54:57]
	v_exp_f32_e32 v107, v107
	s_waitcnt lgkmcnt(5)
	v_mfma_f32_16x16x32_bf16 v[58:61], v[206:209], v[130:133], v[58:61]
	v_exp_f32_e32 v108, v108
	ds_read_b128 v[182:185], v234 offset:53248
	v_mfma_f32_16x16x32_bf16 v[62:65], v[206:209], v[134:137], v[62:65]
	v_exp_f32_e32 v109, v109
	s_waitcnt lgkmcnt(4)
	v_mfma_f32_16x16x32_bf16 v[66:69], v[210:213], v[130:133], v[66:69]
	v_exp_f32_e32 v110, v110
	ds_read_b128 v[186:189], v234 offset:57344
	v_mfma_f32_16x16x32_bf16 v[70:73], v[210:213], v[134:137], v[70:73]
	v_exp_f32_e32 v111, v111
	s_waitcnt lgkmcnt(3)
	v_mfma_f32_16x16x32_bf16 v[74:77], v[214:217], v[130:133], v[74:77]
	v_exp_f32_e32 v112, v112
	ds_read_b128 v[190:193], v234 offset:61440
	v_mfma_f32_16x16x32_bf16 v[78:81], v[214:217], v[134:137], v[78:81]
	v_exp_f32_e32 v113, v113
	s_waitcnt vmcnt(0)
	s_barrier
	s_waitcnt lgkmcnt(3)
	v_mfma_f32_16x16x32_bf16 v[114:117], v[178:181], v[146:149], v[2:5]
	v_add_f32_e32 v250, v82, v250
	v_mfma_f32_16x16x32_bf16 v[118:121], v[178:181], v[162:165], v[2:5]
	ds_read_b128 v[178:181], v235 offset:49152
	v_add_f32_e32 v250, v83, v250
	v_add_f32_e32 v250, v84, v250
	s_waitcnt lgkmcnt(3)
	v_mfma_f32_16x16x32_bf16 v[122:125], v[182:185], v[146:149], v[2:5]
	v_add_f32_e32 v250, v85, v250
	v_mfma_f32_16x16x32_bf16 v[126:129], v[182:185], v[162:165], v[2:5]
	ds_read_b128 v[182:185], v235 offset:53248
	v_add_f32_e32 v250, v90, v250
	v_add_f32_e32 v250, v91, v250
	s_waitcnt lgkmcnt(3)
	v_mfma_f32_16x16x32_bf16 v[130:133], v[186:189], v[146:149], v[2:5]
	v_add_f32_e32 v250, v92, v250
	v_mfma_f32_16x16x32_bf16 v[134:137], v[186:189], v[162:165], v[2:5]
	ds_read_b128 v[186:189], v235 offset:57344
	v_add_f32_e32 v250, v93, v250
	v_cvt_pk_bf16_f32 v82, v82, v83
	s_waitcnt lgkmcnt(3)
	v_mfma_f32_16x16x32_bf16 v[138:141], v[190:193], v[146:149], v[2:5]
	v_cvt_pk_bf16_f32 v83, v84, v85
	v_mfma_f32_16x16x32_bf16 v[142:145], v[190:193], v[162:165], v[2:5]
	ds_read_b128 v[190:193], v235 offset:61440
	v_cvt_pk_bf16_f32 v84, v90, v91
	v_cvt_pk_bf16_f32 v85, v92, v93
	s_waitcnt lgkmcnt(3)
	v_mfma_f32_16x16x32_bf16 v[114:117], v[178:181], v[150:153], v[114:117]
	v_add_f32_e32 v251, v86, v251
	v_mfma_f32_16x16x32_bf16 v[118:121], v[178:181], v[166:169], v[118:121]
	ds_read_b128 v[178:181], v236 offset:49152
	v_add_f32_e32 v251, v87, v251
	v_add_f32_e32 v251, v88, v251
	s_waitcnt lgkmcnt(3)
	v_mfma_f32_16x16x32_bf16 v[122:125], v[182:185], v[150:153], v[122:125]
	v_add_f32_e32 v251, v89, v251
	v_mfma_f32_16x16x32_bf16 v[126:129], v[182:185], v[166:169], v[126:129]
	ds_read_b128 v[182:185], v236 offset:53248
	v_add_f32_e32 v251, v94, v251
	v_add_f32_e32 v251, v95, v251
	s_waitcnt lgkmcnt(3)
; #define SBAR() __builtin_amdgcn_sched_barrier(0)
; __device__ __forceinline__ void qkt(f32x16& p0, f32x16& p1, const bf16* Ks, const bf16x8* qr, int r32, int hi, const f32x16& negm) {
; #pragma unroll
;   for (int d0 = 0; d0 < 8; ++d0) { int cb = (d0 * 16 + hi * 8) * 2;
;     bf16x8 b0 = *reinterpret_cast<const bf16x8*>((const char*)Ks + KSWZ(r32, cb));
;     bf16x8 b1 = *reinterpret_cast<const bf16x8*>((const char*)Ks + KSWZ(32 + r32, cb));
;     if (d0 == 0) { p0 = __builtin_amdgcn_mfma_f32_32x32x16_bf16(b0, qr[0], negm, 0, 0, 0); p1 = __builtin_amdgcn_mfma_f32_32x32x16_bf16(b1, qr[0], negm, 0, 0, 0); }
;     else { p0 = __builtin_amdgcn_mfma_f32_32x32x16_bf16(b0, qr[d0], p0, 0, 0, 0); p1 = __builtin_amdgcn_mfma_f32_32x32x16_bf16(b1, qr[d0], p1, 0, 0, 0); } }
; }
; __device__ __forceinline__ int v_st(int k, int c) { const int kk = (k & ~0xC) | ((k & 4) << 1) | ((k & 8) >> 1); return ((kk >> 3) * 4 + (c >> 5)) * 512 + ((kk & 7) * 32 + (c & 31)) * 2; }
; __device__ __forceinline__ int v_rd_base(int lane) { return ((lane & 3) << 3) | (((lane >> 2) & 3) << 6) | (((lane >> 4) & 1) << 5) | (((lane >> 5) & 1) << 8); }
; template <int OFF> __device__ __forceinline__ s16x4 tr_read(int vb) {
;   s16x4 r; asm volatile("ds_read_b64_tr_b16 %0, %1 offset:%2" : "=&v"(r) : "v"(vb), "i"(OFF) : "memory"); return r;
; }
; template <int D0> __device__ __forceinline__ void pv_one(f32x16& od, int vb, bf16x8 pa0, bf16x8 pa1, bf16x8 pa2, bf16x8 pa3) {
;   const s16x4 l0 = tr_read<v_rd_off(D0, 0, 0)>(vb), h0 = tr_read<v_rd_off(D0, 0, 1)>(vb), l1 = tr_read<v_rd_off(D0, 1, 0)>(vb), h1 = tr_read<v_rd_off(D0, 1, 1)>(vb);
;   const s16x4 l2 = tr_read<v_rd_off(D0, 2, 0)>(vb), h2 = tr_read<v_rd_off(D0, 2, 1)>(vb), l3 = tr_read<v_rd_off(D0, 3, 0)>(vb), h3 = tr_read<v_rd_off(D0, 3, 1)>(vb);
;   asm volatile("s_waitcnt lgkmcnt(0)" ::: "memory"); SBAR();
;     ...
;   od = __builtin_amdgcn_mfma_f32_32x32x16_bf16(pa0, PK(l0, h0), od, 0, 0, 0);
;   od = __builtin_amdgcn_mfma_f32_32x32x16_bf16(pa1, PK(l1, h1), od, 0, 0, 0);
;   od = __builtin_amdgcn_mfma_f32_32x32x16_bf16(pa2, PK(l2, h2), od, 0, 0, 0);
;   od = __builtin_amdgcn_mfma_f32_32x32x16_bf16(pa3, PK(l3, h3), od, 0, 0, 0);
;     ...
; }
; __device__ __forceinline__ void pv_d0(f32x16* o, int vb, bf16x8 pa0, bf16x8 pa1, bf16x8 pa2, bf16x8 pa3) {
	v_mfma_f32_16x16x32_bf16 v[130:133], v[186:189], v[150:153], v[130:133]
	v_add_f32_e32 v251, v96, v251
	v_mfma_f32_16x16x32_bf16 v[134:137], v[186:189], v[166:169], v[134:137]
	ds_read_b128 v[186:189], v236 offset:57344
	v_add_f32_e32 v251, v97, v251
	v_cvt_pk_bf16_f32 v86, v86, v87
	s_waitcnt lgkmcnt(3)
	v_mfma_f32_16x16x32_bf16 v[138:141], v[190:193], v[150:153], v[138:141]
	v_cvt_pk_bf16_f32 v87, v88, v89
	v_mfma_f32_16x16x32_bf16 v[142:145], v[190:193], v[166:169], v[142:145]
	ds_read_b128 v[190:193], v236 offset:61440
	v_cvt_pk_bf16_f32 v88, v94, v95
	v_cvt_pk_bf16_f32 v89, v96, v97
	s_waitcnt lgkmcnt(3)
	v_mfma_f32_16x16x32_bf16 v[114:117], v[178:181], v[154:157], v[114:117]
	v_add_f32_e32 v250, v98, v250
	v_mfma_f32_16x16x32_bf16 v[118:121], v[178:181], v[170:173], v[118:121]
	ds_read_b128 v[178:181], v237 offset:49152
	v_add_f32_e32 v250, v99, v250
	v_add_f32_e32 v250, v100, v250
	s_waitcnt lgkmcnt(3)
	v_mfma_f32_16x16x32_bf16 v[122:125], v[182:185], v[154:157], v[122:125]
	v_add_f32_e32 v250, v101, v250
	v_mfma_f32_16x16x32_bf16 v[126:129], v[182:185], v[170:173], v[126:129]
	ds_read_b128 v[182:185], v237 offset:53248
	v_add_f32_e32 v250, v106, v250
	v_add_f32_e32 v250, v107, v250
	s_waitcnt lgkmcnt(3)
	v_mfma_f32_16x16x32_bf16 v[130:133], v[186:189], v[154:157], v[130:133]
	v_add_f32_e32 v250, v108, v250
	ds_read_b64_tr_b16 v[202:203], v238 offset:32768
	ds_read_b64_tr_b16 v[204:205], v238 offset:36864
	v_mfma_f32_16x16x32_bf16 v[134:137], v[186:189], v[170:173], v[134:137]
	ds_read_b128 v[186:189], v237 offset:57344
	v_add_f32_e32 v250, v109, v250
	v_cvt_pk_bf16_f32 v98, v98, v99
	s_waitcnt lgkmcnt(5)
	v_mfma_f32_16x16x32_bf16 v[138:141], v[190:193], v[154:157], v[138:141]
	v_cvt_pk_bf16_f32 v99, v100, v101
	ds_read_b64_tr_b16 v[206:207], v239 offset:32768
	ds_read_b64_tr_b16 v[208:209], v239 offset:36864
	v_mfma_f32_16x16x32_bf16 v[142:145], v[190:193], v[170:173], v[142:145]
	ds_read_b128 v[190:193], v237 offset:61440
	v_cvt_pk_bf16_f32 v100, v106, v107
	v_cvt_pk_bf16_f32 v101, v108, v109
	s_waitcnt lgkmcnt(7)
	v_mfma_f32_16x16x32_bf16 v[114:117], v[178:181], v[158:161], v[114:117]
	v_add_f32_e32 v251, v102, v251
	ds_read_b64_tr_b16 v[210:211], v240 offset:32768
	ds_read_b64_tr_b16 v[212:213], v240 offset:36864
	v_mfma_f32_16x16x32_bf16 v[118:121], v[178:181], v[174:177], v[118:121]
	v_add_f32_e32 v251, v103, v251
	v_add_f32_e32 v251, v104, v251
	s_waitcnt lgkmcnt(8)
	v_mfma_f32_16x16x32_bf16 v[122:125], v[182:185], v[158:161], v[122:125]
	v_add_f32_e32 v251, v105, v251
	ds_read_b64_tr_b16 v[214:215], v241 offset:32768
	ds_read_b64_tr_b16 v[216:217], v241 offset:36864
	v_mfma_f32_16x16x32_bf16 v[126:129], v[182:185], v[174:177], v[126:129]
	v_add_f32_e32 v251, v110, v251
	v_add_f32_e32 v251, v111, v251
	s_waitcnt lgkmcnt(7)
	v_mfma_f32_16x16x32_bf16 v[130:133], v[186:189], v[158:161], v[130:133]
	v_add_f32_e32 v251, v112, v251
	ds_read_b64_tr_b16 v[218:219], v242 offset:32768
	ds_read_b64_tr_b16 v[220:221], v242 offset:36864
	v_mfma_f32_16x16x32_bf16 v[134:137], v[186:189], v[174:177], v[134:137]
	v_add_f32_e32 v251, v113, v251
	v_cvt_pk_bf16_f32 v102, v102, v103
	s_waitcnt lgkmcnt(6)
	v_mfma_f32_16x16x32_bf16 v[138:141], v[190:193], v[158:161], v[138:141]
	v_cvt_pk_bf16_f32 v103, v104, v105
	ds_read_b64_tr_b16 v[222:223], v243 offset:32768
	ds_read_b64_tr_b16 v[224:225], v243 offset:36864
	v_mfma_f32_16x16x32_bf16 v[142:145], v[190:193], v[174:177], v[142:145]
	v_cvt_pk_bf16_f32 v104, v110, v111
	v_cvt_pk_bf16_f32 v105, v112, v113
	v_mfma_f32_16x16x32_bf16 v[18:21], v[202:205], v[82:85], v[18:21]
	v_exp_f32_e32 v114, v114
	v_mfma_f32_16x16x32_bf16 v[22:25], v[202:205], v[86:89], v[22:25]
	ds_read_b64_tr_b16 v[202:203], v244 offset:32768
	ds_read_b64_tr_b16 v[204:205], v244 offset:36864
	v_exp_f32_e32 v115, v115
	v_mfma_f32_16x16x32_bf16 v[26:29], v[206:209], v[82:85], v[26:29]
	v_exp_f32_e32 v116, v116
	v_mfma_f32_16x16x32_bf16 v[30:33], v[206:209], v[86:89], v[30:33]
	ds_read_b64_tr_b16 v[206:207], v245 offset:32768
	ds_read_b64_tr_b16 v[208:209], v245 offset:36864
	v_exp_f32_e32 v117, v117
	s_waitcnt lgkmcnt(10)
	v_mfma_f32_16x16x32_bf16 v[34:37], v[210:213], v[82:85], v[34:37]
	v_exp_f32_e32 v118, v118
	v_mfma_f32_16x16x32_bf16 v[38:41], v[210:213], v[86:89], v[38:41]
	ds_read_b64_tr_b16 v[210:211], v238 offset:40960
	ds_read_b64_tr_b16 v[212:213], v238 offset:45056
	v_exp_f32_e32 v119, v119
	s_waitcnt lgkmcnt(10)
	v_mfma_f32_16x16x32_bf16 v[42:45], v[214:217], v[82:85], v[42:45]
	v_exp_f32_e32 v120, v120
	v_mfma_f32_16x16x32_bf16 v[46:49], v[214:217], v[86:89], v[46:49]
	ds_read_b64_tr_b16 v[214:215], v239 offset:40960
	ds_read_b64_tr_b16 v[216:217], v239 offset:45056
	v_exp_f32_e32 v121, v121
	s_waitcnt lgkmcnt(10)
	v_mfma_f32_16x16x32_bf16 v[50:53], v[218:221], v[82:85], v[50:53]
	v_exp_f32_e32 v122, v122
	v_mfma_f32_16x16x32_bf16 v[54:57], v[218:221], v[86:89], v[54:57]
	ds_read_b64_tr_b16 v[218:219], v240 offset:40960
	ds_read_b64_tr_b16 v[220:221], v240 offset:45056
	v_exp_f32_e32 v123, v123
	s_waitcnt lgkmcnt(10)
	v_mfma_f32_16x16x32_bf16 v[58:61], v[222:225], v[82:85], v[58:61]
	v_exp_f32_e32 v124, v124
	v_mfma_f32_16x16x32_bf16 v[62:65], v[222:225], v[86:89], v[62:65]
	ds_read_b64_tr_b16 v[222:223], v241 offset:40960
	ds_read_b64_tr_b16 v[224:225], v241 offset:45056
	v_exp_f32_e32 v125, v125
	s_waitcnt lgkmcnt(10)
	v_mfma_f32_16x16x32_bf16 v[66:69], v[202:205], v[82:85], v[66:69]
	v_exp_f32_e32 v126, v126
	v_mfma_f32_16x16x32_bf16 v[70:73], v[202:205], v[86:89], v[70:73]
	ds_read_b64_tr_b16 v[202:203], v242 offset:40960
	ds_read_b64_tr_b16 v[204:205], v242 offset:45056
	v_exp_f32_e32 v127, v127
	s_waitcnt lgkmcnt(10)
; #define SBAR() __builtin_amdgcn_sched_barrier(0)
; template <int D0> __device__ __forceinline__ void pv_one(f32x16& od, int vb, bf16x8 pa0, bf16x8 pa1, bf16x8 pa2, bf16x8 pa3) {
;   const s16x4 l0 = tr_read<v_rd_off(D0, 0, 0)>(vb), h0 = tr_read<v_rd_off(D0, 0, 1)>(vb), l1 = tr_read<v_rd_off(D0, 1, 0)>(vb), h1 = tr_read<v_rd_off(D0, 1, 1)>(vb);
;   const s16x4 l2 = tr_read<v_rd_off(D0, 2, 0)>(vb), h2 = tr_read<v_rd_off(D0, 2, 1)>(vb), l3 = tr_read<v_rd_off(D0, 3, 0)>(vb), h3 = tr_read<v_rd_off(D0, 3, 1)>(vb);
;   asm volatile("s_waitcnt lgkmcnt(0)" ::: "memory"); SBAR();
;     ...
;   od = __builtin_amdgcn_mfma_f32_32x32x16_bf16(pa0, PK(l0, h0), od, 0, 0, 0);
;   od = __builtin_amdgcn_mfma_f32_32x32x16_bf16(pa1, PK(l1, h1), od, 0, 0, 0);
;   od = __builtin_amdgcn_mfma_f32_32x32x16_bf16(pa2, PK(l2, h2), od, 0, 0, 0);
;   od = __builtin_amdgcn_mfma_f32_32x32x16_bf16(pa3, PK(l3, h3), od, 0, 0, 0);
;     ...
; }
; __device__ __forceinline__ void pv_d0(f32x16* o, int vb, bf16x8 pa0, bf16x8 pa1, bf16x8 pa2, bf16x8 pa3) {
;   pv_one<0>(o[0], vb, pa0, pa1, pa2, pa3); pv_one<1>(o[1], vb, pa0, pa1, pa2, pa3); pv_one<2>(o[2], vb, pa0, pa1, pa2, pa3); pv_one<3>(o[3], vb, pa0, pa1, pa2, pa3);
; template <typename TQ> ...
;     ...
;   finishSM(pB0, pB1, l_reg, pa0, pa1, pa2, pa3); SBAR();
;   pv_d0(o, vb0 + (int)SHM_V, pa0, pa1, pa2, pa3);
	v_mfma_f32_16x16x32_bf16 v[74:77], v[206:209], v[82:85], v[74:77]
	v_exp_f32_e32 v128, v128
	v_mfma_f32_16x16x32_bf16 v[78:81], v[206:209], v[86:89], v[78:81]
	ds_read_b64_tr_b16 v[206:207], v243 offset:40960
	ds_read_b64_tr_b16 v[208:209], v243 offset:45056
	v_exp_f32_e32 v129, v129
	s_waitcnt lgkmcnt(10)
	v_mfma_f32_16x16x32_bf16 v[18:21], v[210:213], v[98:101], v[18:21]
	v_exp_f32_e32 v130, v130
	v_mfma_f32_16x16x32_bf16 v[22:25], v[210:213], v[102:105], v[22:25]
	ds_read_b64_tr_b16 v[210:211], v244 offset:40960
	ds_read_b64_tr_b16 v[212:213], v244 offset:45056
	v_exp_f32_e32 v131, v131
	s_waitcnt lgkmcnt(10)
	v_mfma_f32_16x16x32_bf16 v[26:29], v[214:217], v[98:101], v[26:29]
	v_exp_f32_e32 v132, v132
	v_mfma_f32_16x16x32_bf16 v[30:33], v[214:217], v[102:105], v[30:33]
	ds_read_b64_tr_b16 v[214:215], v245 offset:40960
	ds_read_b64_tr_b16 v[216:217], v245 offset:45056
	v_exp_f32_e32 v133, v133
	s_waitcnt lgkmcnt(10)
	v_mfma_f32_16x16x32_bf16 v[34:37], v[218:221], v[98:101], v[34:37]
	v_exp_f32_e32 v134, v134
	v_mfma_f32_16x16x32_bf16 v[38:41], v[218:221], v[102:105], v[38:41]
	v_exp_f32_e32 v135, v135
	s_waitcnt lgkmcnt(8)
	v_mfma_f32_16x16x32_bf16 v[42:45], v[222:225], v[98:101], v[42:45]
	v_exp_f32_e32 v136, v136
	v_mfma_f32_16x16x32_bf16 v[46:49], v[222:225], v[102:105], v[46:49]
	v_exp_f32_e32 v137, v137
	s_waitcnt lgkmcnt(6)
	v_mfma_f32_16x16x32_bf16 v[50:53], v[202:205], v[98:101], v[50:53]
	v_exp_f32_e32 v138, v138
	v_mfma_f32_16x16x32_bf16 v[54:57], v[202:205], v[102:105], v[54:57]
	v_exp_f32_e32 v139, v139
	s_waitcnt lgkmcnt(4)
	v_mfma_f32_16x16x32_bf16 v[58:61], v[206:209], v[98:101], v[58:61]
	v_exp_f32_e32 v140, v140
	v_mfma_f32_16x16x32_bf16 v[62:65], v[206:209], v[102:105], v[62:65]
	v_exp_f32_e32 v141, v141
	s_waitcnt lgkmcnt(2)
	v_mfma_f32_16x16x32_bf16 v[66:69], v[210:213], v[98:101], v[66:69]
	v_exp_f32_e32 v142, v142
	v_mfma_f32_16x16x32_bf16 v[70:73], v[210:213], v[102:105], v[70:73]
	v_exp_f32_e32 v143, v143
	s_waitcnt lgkmcnt(0)
	v_mfma_f32_16x16x32_bf16 v[74:77], v[214:217], v[98:101], v[74:77]
	v_exp_f32_e32 v144, v144
	v_mfma_f32_16x16x32_bf16 v[78:81], v[214:217], v[102:105], v[78:81]
	v_exp_f32_e32 v145, v145
	s_waitcnt vmcnt(0)
	v_add_f32_e32 v250, v114, v250
	v_add_f32_e32 v250, v115, v250
	v_add_f32_e32 v250, v116, v250
	v_add_f32_e32 v250, v117, v250
	v_add_f32_e32 v250, v122, v250
	v_add_f32_e32 v250, v123, v250
	v_add_f32_e32 v250, v124, v250
	v_add_f32_e32 v250, v125, v250
	v_cvt_pk_bf16_f32 v114, v114, v115
	v_cvt_pk_bf16_f32 v115, v116, v117
	v_cvt_pk_bf16_f32 v116, v122, v123
	v_cvt_pk_bf16_f32 v117, v124, v125
	v_add_f32_e32 v251, v118, v251
	v_add_f32_e32 v251, v119, v251
	v_add_f32_e32 v251, v120, v251
	v_add_f32_e32 v251, v121, v251
	v_add_f32_e32 v251, v126, v251
	v_add_f32_e32 v251, v127, v251
	v_add_f32_e32 v251, v128, v251
	v_add_f32_e32 v251, v129, v251
	v_cvt_pk_bf16_f32 v118, v118, v119
	v_cvt_pk_bf16_f32 v119, v120, v121
	v_cvt_pk_bf16_f32 v120, v126, v127
	v_cvt_pk_bf16_f32 v121, v128, v129
	v_add_f32_e32 v250, v130, v250
	v_add_f32_e32 v250, v131, v250
	v_add_f32_e32 v250, v132, v250
	v_add_f32_e32 v250, v133, v250
	v_add_f32_e32 v250, v138, v250
	v_add_f32_e32 v250, v139, v250
	v_add_f32_e32 v250, v140, v250
	v_add_f32_e32 v250, v141, v250
	v_cvt_pk_bf16_f32 v130, v130, v131
	v_cvt_pk_bf16_f32 v131, v132, v133
	v_cvt_pk_bf16_f32 v132, v138, v139
	v_cvt_pk_bf16_f32 v133, v140, v141
	v_add_f32_e32 v251, v134, v251
	v_add_f32_e32 v251, v135, v251
	v_add_f32_e32 v251, v136, v251
	v_add_f32_e32 v251, v137, v251
	v_add_f32_e32 v251, v142, v251
	v_add_f32_e32 v251, v143, v251
	v_add_f32_e32 v251, v144, v251
	v_add_f32_e32 v251, v145, v251
	v_cvt_pk_bf16_f32 v134, v134, v135
	v_cvt_pk_bf16_f32 v135, v136, v137
	v_cvt_pk_bf16_f32 v136, v142, v143
	v_cvt_pk_bf16_f32 v137, v144, v145
	ds_read_b64_tr_b16 v[202:203], v238 offset:49152
	ds_read_b64_tr_b16 v[204:205], v238 offset:53248
	ds_read_b64_tr_b16 v[206:207], v239 offset:49152
	ds_read_b64_tr_b16 v[208:209], v239 offset:53248
	ds_read_b64_tr_b16 v[210:211], v240 offset:49152
	ds_read_b64_tr_b16 v[212:213], v240 offset:53248
	ds_read_b64_tr_b16 v[214:215], v241 offset:49152
	ds_read_b64_tr_b16 v[216:217], v241 offset:53248
	ds_read_b64_tr_b16 v[218:219], v242 offset:49152
	ds_read_b64_tr_b16 v[220:221], v242 offset:53248
	ds_read_b64_tr_b16 v[222:223], v243 offset:49152
	ds_read_b64_tr_b16 v[224:225], v243 offset:53248
	s_waitcnt lgkmcnt(10)
	v_mfma_f32_16x16x32_bf16 v[18:21], v[202:205], v[114:117], v[18:21]
	v_mfma_f32_16x16x32_bf16 v[22:25], v[202:205], v[118:121], v[22:25]
	ds_read_b64_tr_b16 v[202:203], v244 offset:49152
	ds_read_b64_tr_b16 v[204:205], v244 offset:53248
	s_waitcnt lgkmcnt(10)
	v_mfma_f32_16x16x32_bf16 v[26:29], v[206:209], v[114:117], v[26:29]
	v_mfma_f32_16x16x32_bf16 v[30:33], v[206:209], v[118:121], v[30:33]
	ds_read_b64_tr_b16 v[206:207], v245 offset:49152
	ds_read_b64_tr_b16 v[208:209], v245 offset:53248
	s_waitcnt lgkmcnt(10)
	v_mfma_f32_16x16x32_bf16 v[34:37], v[210:213], v[114:117], v[34:37]
	v_mfma_f32_16x16x32_bf16 v[38:41], v[210:213], v[118:121], v[38:41]
	ds_read_b64_tr_b16 v[210:211], v238 offset:57344
	ds_read_b64_tr_b16 v[212:213], v238 offset:61440
	s_waitcnt lgkmcnt(10)
	v_mfma_f32_16x16x32_bf16 v[42:45], v[214:217], v[114:117], v[42:45]
	v_mfma_f32_16x16x32_bf16 v[46:49], v[214:217], v[118:121], v[46:49]
	ds_read_b64_tr_b16 v[214:215], v239 offset:57344
	ds_read_b64_tr_b16 v[216:217], v239 offset:61440
	s_waitcnt lgkmcnt(10)
	v_mfma_f32_16x16x32_bf16 v[50:53], v[218:221], v[114:117], v[50:53]
	v_mfma_f32_16x16x32_bf16 v[54:57], v[218:221], v[118:121], v[54:57]
	ds_read_b64_tr_b16 v[218:219], v240 offset:57344
	ds_read_b64_tr_b16 v[220:221], v240 offset:61440
	s_waitcnt lgkmcnt(10)
; __device__ __forceinline__ int crow(int r, int hi) { return (r & 3) + 8 * (r >> 2) + 4 * hi; }
; template <typename TQ> ...
;     ...
;   pv_d0(o, vb0 + (int)SHM_V, pa0, pa1, pa2, pa3);
;   if (hi == 0) li_l[r32] = l_reg; asm volatile("s_waitcnt lgkmcnt(0)" ::: "memory");
;   float rli[16];
; #pragma unroll
;   for (int r = 0; r < 16; ++r) rli[r] = __builtin_amdgcn_rcpf(li_l[crow(r, hi)]);
;   int le = (int)(threadIdx.x & 63u); asm volatile("" : "+v"(le));
;   const int r32e = le & 31, hie = le >> 5;
;   bf16* Ow = Ob + (long)(wid * QBLK) * LDO;
; #pragma unroll
;   for (int r = 0; r < 16; ++r) { int orow = crow(r, hie);
;     for (int d0 = 0; d0 < 4; ++d0) Ow[(long)orow * LDO + d0 * 32 + r32e] = __float2bfloat16(o[d0][r] * rli[r]); }
	v_mfma_f32_16x16x32_bf16 v[58:61], v[222:225], v[114:117], v[58:61]
	v_mfma_f32_16x16x32_bf16 v[62:65], v[222:225], v[118:121], v[62:65]
	ds_read_b64_tr_b16 v[222:223], v241 offset:57344
	ds_read_b64_tr_b16 v[224:225], v241 offset:61440
	s_waitcnt lgkmcnt(10)
	v_mfma_f32_16x16x32_bf16 v[66:69], v[202:205], v[114:117], v[66:69]
	v_mfma_f32_16x16x32_bf16 v[70:73], v[202:205], v[118:121], v[70:73]
	ds_read_b64_tr_b16 v[202:203], v242 offset:57344
	ds_read_b64_tr_b16 v[204:205], v242 offset:61440
	s_waitcnt lgkmcnt(10)
	v_mfma_f32_16x16x32_bf16 v[74:77], v[206:209], v[114:117], v[74:77]
	v_mfma_f32_16x16x32_bf16 v[78:81], v[206:209], v[118:121], v[78:81]
	ds_read_b64_tr_b16 v[206:207], v243 offset:57344
	ds_read_b64_tr_b16 v[208:209], v243 offset:61440
	s_waitcnt lgkmcnt(10)
	v_mfma_f32_16x16x32_bf16 v[18:21], v[210:213], v[130:133], v[18:21]
	v_mfma_f32_16x16x32_bf16 v[22:25], v[210:213], v[134:137], v[22:25]
	ds_read_b64_tr_b16 v[210:211], v244 offset:57344
	ds_read_b64_tr_b16 v[212:213], v244 offset:61440
	s_waitcnt lgkmcnt(10)
	v_mfma_f32_16x16x32_bf16 v[26:29], v[214:217], v[130:133], v[26:29]
	v_mfma_f32_16x16x32_bf16 v[30:33], v[214:217], v[134:137], v[30:33]
	ds_read_b64_tr_b16 v[214:215], v245 offset:57344
	ds_read_b64_tr_b16 v[216:217], v245 offset:61440
	s_waitcnt lgkmcnt(10)
	v_mfma_f32_16x16x32_bf16 v[34:37], v[218:221], v[130:133], v[34:37]
	v_mfma_f32_16x16x32_bf16 v[38:41], v[218:221], v[134:137], v[38:41]
	s_waitcnt lgkmcnt(8)
	v_mfma_f32_16x16x32_bf16 v[42:45], v[222:225], v[130:133], v[42:45]
	v_mfma_f32_16x16x32_bf16 v[46:49], v[222:225], v[134:137], v[46:49]
	s_waitcnt lgkmcnt(6)
	v_mfma_f32_16x16x32_bf16 v[50:53], v[202:205], v[130:133], v[50:53]
	v_mfma_f32_16x16x32_bf16 v[54:57], v[202:205], v[134:137], v[54:57]
	s_waitcnt lgkmcnt(4)
	v_mfma_f32_16x16x32_bf16 v[58:61], v[206:209], v[130:133], v[58:61]
	v_mfma_f32_16x16x32_bf16 v[62:65], v[206:209], v[134:137], v[62:65]
	s_waitcnt lgkmcnt(2)
	v_mfma_f32_16x16x32_bf16 v[66:69], v[210:213], v[130:133], v[66:69]
	v_mfma_f32_16x16x32_bf16 v[70:73], v[210:213], v[134:137], v[70:73]
	s_waitcnt lgkmcnt(0)
	v_mfma_f32_16x16x32_bf16 v[74:77], v[214:217], v[130:133], v[74:77]
	v_mfma_f32_16x16x32_bf16 v[78:81], v[214:217], v[134:137], v[78:81]
	s_setprio 0
	ds_swizzle_b32 v6, v250 offset:swizzle(SWAP,16)
	s_waitcnt lgkmcnt(0)
	v_add_f32_e32 v250, v250, v6
	v_mov_b32_e32 v6, v250
	s_nop 1
	v_permlane32_swap_b32_e32 v250, v6
	v_add_f32_e32 v250, v250, v6
	v_rcp_f32_e32 v250, v250
	ds_swizzle_b32 v6, v251 offset:swizzle(SWAP,16)
	s_waitcnt lgkmcnt(0)
	v_add_f32_e32 v251, v251, v6
	v_mov_b32_e32 v6, v251
	s_nop 1
	v_permlane32_swap_b32_e32 v251, v6
	v_add_f32_e32 v251, v251, v6
	v_rcp_f32_e32 v251, v251
	s_add_u32 s12, s71, s48
	s_addc_u32 s13, s72, s49
	v_add_u32_e32 v201, s52, v16
	v_lshlrev_b32_e32 v201, 11, v201
	v_lshl_or_b32 v7, v17, 3, v201
	v_add_u32_e32 v200, 0x8000, v7
	v_mul_f32_e32 v18, v18, v250
	v_mul_f32_e32 v19, v19, v250
	v_mul_f32_e32 v20, v20, v250
	v_mul_f32_e32 v21, v21, v250
	v_cvt_pk_bf16_f32 v18, v18, v19
	v_cvt_pk_bf16_f32 v19, v20, v21
	global_store_dwordx2 v7, v[18:19], s[12:13] offset:0
	v_mul_f32_e32 v22, v22, v251
	v_mul_f32_e32 v23, v23, v251
	v_mul_f32_e32 v24, v24, v251
	v_mul_f32_e32 v25, v25, v251
	v_cvt_pk_bf16_f32 v22, v22, v23
	v_cvt_pk_bf16_f32 v23, v24, v25
	global_store_dwordx2 v200, v[22:23], s[12:13] offset:0
	v_mul_f32_e32 v26, v26, v250
	v_mul_f32_e32 v27, v27, v250
	v_mul_f32_e32 v28, v28, v250
	v_mul_f32_e32 v29, v29, v250
	v_cvt_pk_bf16_f32 v26, v26, v27
	v_cvt_pk_bf16_f32 v27, v28, v29
	global_store_dwordx2 v7, v[26:27], s[12:13] offset:32
	v_mul_f32_e32 v30, v30, v251
	v_mul_f32_e32 v31, v31, v251
	v_mul_f32_e32 v32, v32, v251
	v_mul_f32_e32 v33, v33, v251
	v_cvt_pk_bf16_f32 v30, v30, v31
	v_cvt_pk_bf16_f32 v31, v32, v33
	global_store_dwordx2 v200, v[30:31], s[12:13] offset:32
	v_mul_f32_e32 v34, v34, v250
	v_mul_f32_e32 v35, v35, v250
	v_mul_f32_e32 v36, v36, v250
	v_mul_f32_e32 v37, v37, v250
	v_cvt_pk_bf16_f32 v34, v34, v35
	v_cvt_pk_bf16_f32 v35, v36, v37
	global_store_dwordx2 v7, v[34:35], s[12:13] offset:64
	v_mul_f32_e32 v38, v38, v251
	v_mul_f32_e32 v39, v39, v251
	v_mul_f32_e32 v40, v40, v251
	v_mul_f32_e32 v41, v41, v251
	v_cvt_pk_bf16_f32 v38, v38, v39
	v_cvt_pk_bf16_f32 v39, v40, v41
	global_store_dwordx2 v200, v[38:39], s[12:13] offset:64
	v_mul_f32_e32 v42, v42, v250
	v_mul_f32_e32 v43, v43, v250
	v_mul_f32_e32 v44, v44, v250
	v_mul_f32_e32 v45, v45, v250
	v_cvt_pk_bf16_f32 v42, v42, v43
	v_cvt_pk_bf16_f32 v43, v44, v45
	global_store_dwordx2 v7, v[42:43], s[12:13] offset:96
	v_mul_f32_e32 v46, v46, v251
	v_mul_f32_e32 v47, v47, v251
	v_mul_f32_e32 v48, v48, v251
	v_mul_f32_e32 v49, v49, v251
	v_cvt_pk_bf16_f32 v46, v46, v47
	v_cvt_pk_bf16_f32 v47, v48, v49
	global_store_dwordx2 v200, v[46:47], s[12:13] offset:96
	v_mul_f32_e32 v50, v50, v250
	v_mul_f32_e32 v51, v51, v250
	v_mul_f32_e32 v52, v52, v250
	v_mul_f32_e32 v53, v53, v250
	v_cvt_pk_bf16_f32 v50, v50, v51
	v_cvt_pk_bf16_f32 v51, v52, v53
	global_store_dwordx2 v7, v[50:51], s[12:13] offset:128
	v_mul_f32_e32 v54, v54, v251
	v_mul_f32_e32 v55, v55, v251
	v_mul_f32_e32 v56, v56, v251
	v_mul_f32_e32 v57, v57, v251
	v_cvt_pk_bf16_f32 v54, v54, v55
	v_cvt_pk_bf16_f32 v55, v56, v57
	global_store_dwordx2 v200, v[54:55], s[12:13] offset:128
	v_mul_f32_e32 v58, v58, v250
	v_mul_f32_e32 v59, v59, v250
	v_mul_f32_e32 v60, v60, v250
	v_mul_f32_e32 v61, v61, v250
	v_cvt_pk_bf16_f32 v58, v58, v59
	v_cvt_pk_bf16_f32 v59, v60, v61
	global_store_dwordx2 v7, v[58:59], s[12:13] offset:160
	v_mul_f32_e32 v62, v62, v251
	v_mul_f32_e32 v63, v63, v251
	v_mul_f32_e32 v64, v64, v251
	v_mul_f32_e32 v65, v65, v251
	v_cvt_pk_bf16_f32 v62, v62, v63
	v_cvt_pk_bf16_f32 v63, v64, v65
	global_store_dwordx2 v200, v[62:63], s[12:13] offset:160
	v_mul_f32_e32 v66, v66, v250
	v_mul_f32_e32 v67, v67, v250
	v_mul_f32_e32 v68, v68, v250
	v_mul_f32_e32 v69, v69, v250
	v_cvt_pk_bf16_f32 v66, v66, v67
	v_cvt_pk_bf16_f32 v67, v68, v69
	global_store_dwordx2 v7, v[66:67], s[12:13] offset:192
	v_mul_f32_e32 v70, v70, v251
	v_mul_f32_e32 v71, v71, v251
	v_mul_f32_e32 v72, v72, v251
	v_mul_f32_e32 v73, v73, v251
	v_cvt_pk_bf16_f32 v70, v70, v71
	v_cvt_pk_bf16_f32 v71, v72, v73
	global_store_dwordx2 v200, v[70:71], s[12:13] offset:192
	v_mul_f32_e32 v74, v74, v250
	v_mul_f32_e32 v75, v75, v250
	v_mul_f32_e32 v76, v76, v250
	v_mul_f32_e32 v77, v77, v250
	v_cvt_pk_bf16_f32 v74, v74, v75
	v_cvt_pk_bf16_f32 v75, v76, v77
	global_store_dwordx2 v7, v[74:75], s[12:13] offset:224
	v_mul_f32_e32 v78, v78, v251
	v_mul_f32_e32 v79, v79, v251
	v_mul_f32_e32 v80, v80, v251
	v_mul_f32_e32 v81, v81, v251
	v_cvt_pk_bf16_f32 v78, v78, v79
	v_cvt_pk_bf16_f32 v79, v80, v81
	global_store_dwordx2 v200, v[78:79], s[12:13] offset:224
	s_add_i32 s74, s74, 1
	s_add_i32 s94, s94, 1
	s_cmp_eq_u32 s74, s66
	s_cselect_b64 s[0:1], -1, 0
	s_barrier
	s_branch .LBB0_818
	s_nop 0
